# GEMM K-loops: the next-tile stage loads of a tile's last iteration run with EXEC=0 when the workgroup has no next tile (14 useless LDS-DMA per wave per phase end dropped)
# speedup vs baseline: 1.0076x; 1.0058x over previous
.LBB0_131:
	s_add_u32 s28, s8, s10
	s_addc_u32 s29, s9, s11
	s_add_u32 s34, s28, 0x100
	s_addc_u32 s35, s29, 0
	s_add_u32 s30, s70, s10
	s_addc_u32 s31, s71, s11
	s_add_u32 s28, s28, 0x180
	s_addc_u32 s29, s29, 0
	s_add_i32 s73, 0, 0x10000
	s_add_i32 s76, 0, 0x14000
	v_add_u32_e32 v146, s73, v166
	ds_read_b128 v[148:151], v146
	ds_read_b128 v[152:155], v146 offset:1024
	ds_read_b128 v[156:159], v146 offset:2048
	ds_read_b128 v[160:163], v146 offset:3072
	v_add_u32_e32 v146, s76, v166
	ds_read_b128 v[172:175], v146
	ds_read_b128 v[176:179], v146 offset:1024
	ds_read_b128 v[180:183], v146 offset:2048
	ds_read_b128 v[184:187], v146 offset:3072
	s_cmpk_eq_i32 s10, 0x700
	s_cselect_b64 s[98:99], s[6:7], -1
	s_cselect_b32 s29, s69, s29
	s_cselect_b32 s28, s68, s28
	s_cselect_b32 s31, s21, s31
	s_cselect_b32 s30, s59, s30
	s_cselect_b32 s35, s23, s35
	s_cselect_b32 s34, s58, s34
	v_lshl_add_u64 v[164:165], v[142:143], 0, s[10:11]
	s_add_i32 m0, s41, 0xc000
	ds_read_b128 v[188:191], v171
	ds_read_b128 v[202:205], v171 offset:1024
	ds_read_b128 v[206:209], v171 offset:2048
	ds_read_b128 v[210:213], v171 offset:3072
	ds_read_b128 v[214:217], v171 offset:4096
	ds_read_b128 v[218:221], v171 offset:5120
	ds_read_b128 v[222:225], v171 offset:6144
	ds_read_b128 v[226:229], v171 offset:7168
	global_load_lds_dwordx4 v[164:165], off
	v_lshl_add_u64 v[164:165], v[144:145], 0, s[10:11]
	s_add_i32 m0, s41, 0xe000
	s_nop 0
	global_load_lds_dwordx4 v[164:165], off
	s_waitcnt vmcnt(8)
	s_waitcnt lgkmcnt(0)
	s_setprio 1
	s_barrier
	v_mfma_f32_16x16x32_bf16 v[126:129], v[148:151], v[188:191], v[126:129]
	v_mfma_f32_16x16x32_bf16 v[122:125], v[156:159], v[188:191], v[122:125]
	v_mfma_f32_16x16x32_bf16 v[110:113], v[148:151], v[206:209], v[110:113]
	v_mfma_f32_16x16x32_bf16 v[106:109], v[156:159], v[206:209], v[106:109]
	v_mfma_f32_16x16x32_bf16 v[94:97], v[148:151], v[214:217], v[94:97]
	v_mfma_f32_16x16x32_bf16 v[90:93], v[156:159], v[214:217], v[90:93]
	v_mfma_f32_16x16x32_bf16 v[78:81], v[148:151], v[222:225], v[78:81]
	v_mfma_f32_16x16x32_bf16 v[74:77], v[156:159], v[222:225], v[74:77]
	v_mfma_f32_16x16x32_bf16 v[126:129], v[152:155], v[202:205], v[126:129]
	v_mfma_f32_16x16x32_bf16 v[122:125], v[160:163], v[202:205], v[122:125]
	v_mfma_f32_16x16x32_bf16 v[110:113], v[152:155], v[210:213], v[110:113]
	v_mfma_f32_16x16x32_bf16 v[106:109], v[160:163], v[210:213], v[106:109]
	v_mfma_f32_16x16x32_bf16 v[94:97], v[152:155], v[218:221], v[94:97]
	v_mfma_f32_16x16x32_bf16 v[90:93], v[160:163], v[218:221], v[90:93]
	v_mfma_f32_16x16x32_bf16 v[78:81], v[152:155], v[226:229], v[78:81]
	v_mfma_f32_16x16x32_bf16 v[74:77], v[160:163], v[226:229], v[74:77]
	v_mfma_f32_16x16x32_bf16 v[118:121], v[172:175], v[188:191], v[118:121]
	v_mfma_f32_16x16x32_bf16 v[114:117], v[180:183], v[188:191], v[114:117]
	v_mfma_f32_16x16x32_bf16 v[102:105], v[172:175], v[206:209], v[102:105]
	v_mfma_f32_16x16x32_bf16 v[98:101], v[180:183], v[206:209], v[98:101]
	v_mfma_f32_16x16x32_bf16 v[86:89], v[172:175], v[214:217], v[86:89]
	v_mfma_f32_16x16x32_bf16 v[82:85], v[180:183], v[214:217], v[82:85]
	v_mfma_f32_16x16x32_bf16 v[70:73], v[172:175], v[222:225], v[70:73]
	v_mfma_f32_16x16x32_bf16 v[66:69], v[180:183], v[222:225], v[66:69]
	v_mfma_f32_16x16x32_bf16 v[118:121], v[176:179], v[202:205], v[118:121]
	v_mfma_f32_16x16x32_bf16 v[114:117], v[184:187], v[202:205], v[114:117]
	v_mfma_f32_16x16x32_bf16 v[102:105], v[176:179], v[210:213], v[102:105]
	v_mfma_f32_16x16x32_bf16 v[98:101], v[184:187], v[210:213], v[98:101]
	v_mfma_f32_16x16x32_bf16 v[86:89], v[176:179], v[218:221], v[86:89]
	v_mfma_f32_16x16x32_bf16 v[82:85], v[184:187], v[218:221], v[82:85]
	v_mfma_f32_16x16x32_bf16 v[70:73], v[176:179], v[226:229], v[70:73]
	v_mfma_f32_16x16x32_bf16 v[66:69], v[184:187], v[226:229], v[66:69]
	s_barrier
	s_setprio 0
	s_add_i32 s73, s73, s40
	v_lshl_add_u64 v[164:165], s[30:31], 0, v[134:135]
	s_mov_b32 m0, s73
	ds_read_b128 v[188:191], v171 offset:16384
	ds_read_b128 v[202:205], v171 offset:17408
	ds_read_b128 v[206:209], v171 offset:18432
	ds_read_b128 v[210:213], v171 offset:19456
	ds_read_b128 v[214:217], v171 offset:20480
	ds_read_b128 v[218:221], v171 offset:21504
	ds_read_b128 v[222:225], v171 offset:22528
	ds_read_b128 v[226:229], v171 offset:23552
	s_mov_b64 exec, s[98:99]
	global_load_lds_dwordx4 v[164:165], off
	s_add_i32 m0, s73, 0x2000
	s_add_u32 s74, s30, 0x40000
	v_lshl_add_u64 v[192:193], s[30:31], 0, v[130:131]
	s_addc_u32 s75, s31, 0
	s_add_i32 s73, s76, s40
	global_load_lds_dwordx4 v[192:193], off
	v_lshl_add_u64 v[194:195], s[74:75], 0, v[134:135]
	s_mov_b32 m0, s73
	s_nop 0
	global_load_lds_dwordx4 v[194:195], off
	v_lshl_add_u64 v[194:195], s[74:75], 0, v[130:131]
	s_add_i32 m0, s73, 0x2000
	s_nop 0
	global_load_lds_dwordx4 v[194:195], off
	v_lshl_add_u64 v[194:195], s[34:35], 0, v[136:137]
	s_mov_b32 m0, s41
	s_nop 0
	global_load_lds_dwordx4 v[194:195], off
	v_lshl_add_u64 v[194:195], s[34:35], 0, v[132:133]
	s_mov_b32 m0, s42
	s_nop 0
	global_load_lds_dwordx4 v[194:195], off
	s_mov_b64 exec, -1
	s_waitcnt vmcnt(8)
	s_waitcnt lgkmcnt(0)
	s_setprio 1
	s_barrier
	v_mfma_f32_16x16x32_bf16 v[62:65], v[148:151], v[188:191], v[62:65]
	v_mfma_f32_16x16x32_bf16 v[58:61], v[156:159], v[188:191], v[58:61]
	v_mfma_f32_16x16x32_bf16 v[46:49], v[148:151], v[206:209], v[46:49]
	v_mfma_f32_16x16x32_bf16 v[42:45], v[156:159], v[206:209], v[42:45]
	v_mfma_f32_16x16x32_bf16 v[30:33], v[148:151], v[214:217], v[30:33]
	v_mfma_f32_16x16x32_bf16 v[26:29], v[156:159], v[214:217], v[26:29]
	v_mfma_f32_16x16x32_bf16 v[14:17], v[148:151], v[222:225], v[14:17]
	v_mfma_f32_16x16x32_bf16 v[10:13], v[156:159], v[222:225], v[10:13]
	v_mfma_f32_16x16x32_bf16 v[62:65], v[152:155], v[202:205], v[62:65]
	v_mfma_f32_16x16x32_bf16 v[58:61], v[160:163], v[202:205], v[58:61]
	v_mfma_f32_16x16x32_bf16 v[46:49], v[152:155], v[210:213], v[46:49]
	v_mfma_f32_16x16x32_bf16 v[42:45], v[160:163], v[210:213], v[42:45]
	v_mfma_f32_16x16x32_bf16 v[30:33], v[152:155], v[218:221], v[30:33]
	v_mfma_f32_16x16x32_bf16 v[26:29], v[160:163], v[218:221], v[26:29]
	v_mfma_f32_16x16x32_bf16 v[14:17], v[152:155], v[226:229], v[14:17]
	v_mfma_f32_16x16x32_bf16 v[10:13], v[160:163], v[226:229], v[10:13]
	v_mfma_f32_16x16x32_bf16 v[54:57], v[172:175], v[188:191], v[54:57]
	v_mfma_f32_16x16x32_bf16 v[50:53], v[180:183], v[188:191], v[50:53]
	v_mfma_f32_16x16x32_bf16 v[38:41], v[172:175], v[206:209], v[38:41]
	v_mfma_f32_16x16x32_bf16 v[34:37], v[180:183], v[206:209], v[34:37]
	v_mfma_f32_16x16x32_bf16 v[22:25], v[172:175], v[214:217], v[22:25]
	v_mfma_f32_16x16x32_bf16 v[18:21], v[180:183], v[214:217], v[18:21]
	v_mfma_f32_16x16x32_bf16 v[6:9], v[172:175], v[222:225], v[6:9]
	v_mfma_f32_16x16x32_bf16 v[2:5], v[180:183], v[222:225], v[2:5]
	v_mfma_f32_16x16x32_bf16 v[54:57], v[176:179], v[202:205], v[54:57]
	v_mfma_f32_16x16x32_bf16 v[50:53], v[184:187], v[202:205], v[50:53]
	v_mfma_f32_16x16x32_bf16 v[38:41], v[176:179], v[210:213], v[38:41]
	v_mfma_f32_16x16x32_bf16 v[34:37], v[184:187], v[210:213], v[34:37]
	v_mfma_f32_16x16x32_bf16 v[22:25], v[176:179], v[218:221], v[22:25]
	v_mfma_f32_16x16x32_bf16 v[18:21], v[184:187], v[218:221], v[18:21]
	v_mfma_f32_16x16x32_bf16 v[6:9], v[176:179], v[226:229], v[6:9]
	v_mfma_f32_16x16x32_bf16 v[2:5], v[184:187], v[226:229], v[2:5]
	s_barrier
	s_setprio 0
	s_add_i32 s73, 0, 0x18000
	v_add_u32_e32 v146, s73, v166
	s_add_i32 s74, 0, 0x1c000
	ds_read_b128 v[148:151], v146
	ds_read_b128 v[152:155], v146 offset:1024
	ds_read_b128 v[156:159], v146 offset:2048
	ds_read_b128 v[160:163], v146 offset:3072
	v_add_u32_e32 v146, s74, v166
	ds_read_b128 v[172:175], v146
	ds_read_b128 v[176:179], v146 offset:1024
	ds_read_b128 v[180:183], v146 offset:2048
	ds_read_b128 v[184:187], v146 offset:3072
	s_add_u32 s34, s34, 0x40000
	s_addc_u32 s35, s35, 0
	s_mov_b32 m0, s43
	v_lshl_add_u64 v[194:195], s[34:35], 0, v[136:137]
	ds_read_b128 v[188:191], v171 offset:32768
	ds_read_b128 v[202:205], v171 offset:33792
	ds_read_b128 v[206:209], v171 offset:34816
	ds_read_b128 v[210:213], v171 offset:35840
	ds_read_b128 v[214:217], v171 offset:36864
	ds_read_b128 v[218:221], v171 offset:37888
	ds_read_b128 v[222:225], v171 offset:38912
	ds_read_b128 v[226:229], v171 offset:39936
	s_mov_b64 exec, s[98:99]
	global_load_lds_dwordx4 v[194:195], off
	v_lshl_add_u64 v[194:195], s[34:35], 0, v[132:133]
	s_mov_b32 m0, s44
	s_nop 0
	global_load_lds_dwordx4 v[194:195], off
	s_mov_b64 exec, -1
	s_waitcnt vmcnt(8)
	s_waitcnt lgkmcnt(0)
	s_setprio 1
	s_barrier
	v_mfma_f32_16x16x32_bf16 v[126:129], v[148:151], v[188:191], v[126:129]
	v_mfma_f32_16x16x32_bf16 v[122:125], v[156:159], v[188:191], v[122:125]
	v_mfma_f32_16x16x32_bf16 v[110:113], v[148:151], v[206:209], v[110:113]
	v_mfma_f32_16x16x32_bf16 v[106:109], v[156:159], v[206:209], v[106:109]
	v_mfma_f32_16x16x32_bf16 v[94:97], v[148:151], v[214:217], v[94:97]
	v_mfma_f32_16x16x32_bf16 v[90:93], v[156:159], v[214:217], v[90:93]
	v_mfma_f32_16x16x32_bf16 v[78:81], v[148:151], v[222:225], v[78:81]
	v_mfma_f32_16x16x32_bf16 v[74:77], v[156:159], v[222:225], v[74:77]
	v_mfma_f32_16x16x32_bf16 v[126:129], v[152:155], v[202:205], v[126:129]
	v_mfma_f32_16x16x32_bf16 v[122:125], v[160:163], v[202:205], v[122:125]
	v_mfma_f32_16x16x32_bf16 v[110:113], v[152:155], v[210:213], v[110:113]
	v_mfma_f32_16x16x32_bf16 v[106:109], v[160:163], v[210:213], v[106:109]
	v_mfma_f32_16x16x32_bf16 v[94:97], v[152:155], v[218:221], v[94:97]
	v_mfma_f32_16x16x32_bf16 v[90:93], v[160:163], v[218:221], v[90:93]
	v_mfma_f32_16x16x32_bf16 v[78:81], v[152:155], v[226:229], v[78:81]
	v_mfma_f32_16x16x32_bf16 v[74:77], v[160:163], v[226:229], v[74:77]
	v_mfma_f32_16x16x32_bf16 v[118:121], v[172:175], v[188:191], v[118:121]
	v_mfma_f32_16x16x32_bf16 v[114:117], v[180:183], v[188:191], v[114:117]
	v_mfma_f32_16x16x32_bf16 v[102:105], v[172:175], v[206:209], v[102:105]
	v_mfma_f32_16x16x32_bf16 v[98:101], v[180:183], v[206:209], v[98:101]
	v_mfma_f32_16x16x32_bf16 v[86:89], v[172:175], v[214:217], v[86:89]
	v_mfma_f32_16x16x32_bf16 v[82:85], v[180:183], v[214:217], v[82:85]
	v_mfma_f32_16x16x32_bf16 v[70:73], v[172:175], v[222:225], v[70:73]
	v_mfma_f32_16x16x32_bf16 v[66:69], v[180:183], v[222:225], v[66:69]
	v_mfma_f32_16x16x32_bf16 v[118:121], v[176:179], v[202:205], v[118:121]
	v_mfma_f32_16x16x32_bf16 v[114:117], v[184:187], v[202:205], v[114:117]
	v_mfma_f32_16x16x32_bf16 v[102:105], v[176:179], v[210:213], v[102:105]
	v_mfma_f32_16x16x32_bf16 v[98:101], v[184:187], v[210:213], v[98:101]
	v_mfma_f32_16x16x32_bf16 v[86:89], v[176:179], v[218:221], v[86:89]
	v_mfma_f32_16x16x32_bf16 v[82:85], v[184:187], v[218:221], v[82:85]
	v_mfma_f32_16x16x32_bf16 v[70:73], v[176:179], v[226:229], v[70:73]
	v_mfma_f32_16x16x32_bf16 v[66:69], v[184:187], v[226:229], v[66:69]
	s_barrier
	s_setprio 0
	s_add_i32 s34, s73, s40
	v_lshl_add_u64 v[164:165], v[164:165], 0, s[90:91]
	s_mov_b32 m0, s34
	ds_read_b128 v[188:191], v171 offset:49152
	ds_read_b128 v[202:205], v171 offset:50176
	ds_read_b128 v[206:209], v171 offset:51200
	ds_read_b128 v[210:213], v171 offset:52224
	ds_read_b128 v[214:217], v171 offset:53248
	ds_read_b128 v[218:221], v171 offset:54272
	ds_read_b128 v[222:225], v171 offset:55296
	ds_read_b128 v[226:229], v171 offset:56320
	s_mov_b64 exec, s[98:99]
	global_load_lds_dwordx4 v[164:165], off
	s_add_i32 m0, s34, 0x2000
	s_add_u32 s30, s30, 0x40080
	v_lshl_add_u64 v[164:165], v[192:193], 0, s[90:91]
	s_addc_u32 s31, s31, 0
	s_add_i32 s34, s74, s40
	global_load_lds_dwordx4 v[164:165], off
	v_lshl_add_u64 v[164:165], s[30:31], 0, v[134:135]
	s_mov_b32 m0, s34
	s_nop 0
	global_load_lds_dwordx4 v[164:165], off
	v_lshl_add_u64 v[164:165], s[30:31], 0, v[130:131]
	s_add_i32 m0, s34, 0x2000
	s_nop 0
	global_load_lds_dwordx4 v[164:165], off
	v_lshl_add_u64 v[164:165], s[28:29], 0, v[136:137]
	s_mov_b32 m0, s45
	s_nop 0
	global_load_lds_dwordx4 v[164:165], off
	v_lshl_add_u64 v[164:165], s[28:29], 0, v[132:133]
	s_mov_b32 m0, s51
	s_nop 0
	global_load_lds_dwordx4 v[164:165], off
	s_mov_b64 exec, -1
	s_waitcnt vmcnt(8)
	s_waitcnt lgkmcnt(0)
	s_setprio 1
	s_barrier
	v_mfma_f32_16x16x32_bf16 v[62:65], v[148:151], v[188:191], v[62:65]
	v_mfma_f32_16x16x32_bf16 v[58:61], v[156:159], v[188:191], v[58:61]
	v_mfma_f32_16x16x32_bf16 v[46:49], v[148:151], v[206:209], v[46:49]
	v_mfma_f32_16x16x32_bf16 v[42:45], v[156:159], v[206:209], v[42:45]
	v_mfma_f32_16x16x32_bf16 v[30:33], v[148:151], v[214:217], v[30:33]
	v_mfma_f32_16x16x32_bf16 v[26:29], v[156:159], v[214:217], v[26:29]
	v_mfma_f32_16x16x32_bf16 v[14:17], v[148:151], v[222:225], v[14:17]
	v_mfma_f32_16x16x32_bf16 v[10:13], v[156:159], v[222:225], v[10:13]
	v_mfma_f32_16x16x32_bf16 v[62:65], v[152:155], v[202:205], v[62:65]
	v_mfma_f32_16x16x32_bf16 v[58:61], v[160:163], v[202:205], v[58:61]
	v_mfma_f32_16x16x32_bf16 v[46:49], v[152:155], v[210:213], v[46:49]
	v_mfma_f32_16x16x32_bf16 v[42:45], v[160:163], v[210:213], v[42:45]
	v_mfma_f32_16x16x32_bf16 v[30:33], v[152:155], v[218:221], v[30:33]
	v_mfma_f32_16x16x32_bf16 v[26:29], v[160:163], v[218:221], v[26:29]
	v_mfma_f32_16x16x32_bf16 v[14:17], v[152:155], v[226:229], v[14:17]
	v_mfma_f32_16x16x32_bf16 v[10:13], v[160:163], v[226:229], v[10:13]
	v_mfma_f32_16x16x32_bf16 v[54:57], v[172:175], v[188:191], v[54:57]
	v_mfma_f32_16x16x32_bf16 v[50:53], v[180:183], v[188:191], v[50:53]
	v_mfma_f32_16x16x32_bf16 v[38:41], v[172:175], v[206:209], v[38:41]
	v_mfma_f32_16x16x32_bf16 v[34:37], v[180:183], v[206:209], v[34:37]
	v_mfma_f32_16x16x32_bf16 v[22:25], v[172:175], v[214:217], v[22:25]
	v_mfma_f32_16x16x32_bf16 v[18:21], v[180:183], v[214:217], v[18:21]
	v_mfma_f32_16x16x32_bf16 v[6:9], v[172:175], v[222:225], v[6:9]
	v_mfma_f32_16x16x32_bf16 v[2:5], v[180:183], v[222:225], v[2:5]
	v_mfma_f32_16x16x32_bf16 v[54:57], v[176:179], v[202:205], v[54:57]
	v_mfma_f32_16x16x32_bf16 v[50:53], v[184:187], v[202:205], v[50:53]
	v_mfma_f32_16x16x32_bf16 v[38:41], v[176:179], v[210:213], v[38:41]
	v_mfma_f32_16x16x32_bf16 v[34:37], v[184:187], v[210:213], v[34:37]
	v_mfma_f32_16x16x32_bf16 v[22:25], v[176:179], v[218:221], v[22:25]
	v_mfma_f32_16x16x32_bf16 v[18:21], v[184:187], v[218:221], v[18:21]
	v_mfma_f32_16x16x32_bf16 v[6:9], v[176:179], v[226:229], v[6:9]
	v_mfma_f32_16x16x32_bf16 v[2:5], v[184:187], v[226:229], v[2:5]
	s_barrier
	s_setprio 0
	s_add_i32 s72, s72, 2
	s_add_u32 s10, s10, 0x100
	s_addc_u32 s11, s11, 0
	s_cmp_gt_u32 s72, 13
	s_cbranch_scc0 .LBB0_131

.LBB0_345:
	s_add_u32 s34, s28, s30
	s_addc_u32 s35, s29, s31
	s_add_u32 s38, s34, 0x100
	s_addc_u32 s39, s35, 0
	s_add_u32 s36, s75, s30
	s_addc_u32 s37, s76, s31
	s_add_u32 s34, s34, 0x180
	s_addc_u32 s35, s35, 0
	s_add_i32 s85, 0, 0x10000
	s_add_i32 vcc_lo, 0, 0x14000
	v_add_u32_e32 v0, s85, v152
	ds_read_b128 v[148:151], v0
	ds_read_b128 v[154:157], v0 offset:1024
	ds_read_b128 v[158:161], v0 offset:2048
	ds_read_b128 v[162:165], v0 offset:3072
	v_add_u32_e32 v0, vcc_lo, v152
	ds_read_b128 v[166:169], v0
	ds_read_b128 v[170:173], v0 offset:1024
	ds_read_b128 v[174:177], v0 offset:2048
	ds_read_b128 v[178:181], v0 offset:3072
	s_cmpk_eq_i32 s30, 0x700
	s_cselect_b64 s[98:99], s[18:19], -1
	s_cselect_b32 s35, s74, s35
	s_cselect_b32 s34, s73, s34
	s_cselect_b32 s37, s21, s37
	s_cselect_b32 s36, s72, s36
	s_cselect_b32 s39, s23, s39
	s_cselect_b32 s38, s71, s38
	v_lshl_add_u64 v[194:195], v[144:145], 0, s[30:31]
	s_add_i32 m0, s45, 0xc000
	ds_read_b128 v[182:185], v153
	ds_read_b128 v[186:189], v153 offset:1024
	ds_read_b128 v[190:193], v153 offset:2048
	ds_read_b128 v[202:205], v153 offset:3072
	ds_read_b128 v[206:209], v153 offset:4096
	ds_read_b128 v[210:213], v153 offset:5120
	ds_read_b128 v[214:217], v153 offset:6144
	ds_read_b128 v[218:221], v153 offset:7168
	global_load_lds_dwordx4 v[194:195], off
	v_lshl_add_u64 v[194:195], v[146:147], 0, s[30:31]
	s_add_i32 m0, s45, 0xe000
	s_nop 0
	global_load_lds_dwordx4 v[194:195], off
	s_waitcnt vmcnt(8)
	s_waitcnt lgkmcnt(0)
	s_setprio 1
	s_barrier
	v_mfma_f32_16x16x32_bf16 v[126:129], v[148:151], v[182:185], v[126:129]
	v_mfma_f32_16x16x32_bf16 v[122:125], v[158:161], v[182:185], v[122:125]
	v_mfma_f32_16x16x32_bf16 v[110:113], v[148:151], v[190:193], v[110:113]
	v_mfma_f32_16x16x32_bf16 v[106:109], v[158:161], v[190:193], v[106:109]
	v_mfma_f32_16x16x32_bf16 v[94:97], v[148:151], v[206:209], v[94:97]
	v_mfma_f32_16x16x32_bf16 v[90:93], v[158:161], v[206:209], v[90:93]
	v_mfma_f32_16x16x32_bf16 v[78:81], v[148:151], v[214:217], v[78:81]
	v_mfma_f32_16x16x32_bf16 v[74:77], v[158:161], v[214:217], v[74:77]
	v_mfma_f32_16x16x32_bf16 v[126:129], v[154:157], v[186:189], v[126:129]
	v_mfma_f32_16x16x32_bf16 v[122:125], v[162:165], v[186:189], v[122:125]
	v_mfma_f32_16x16x32_bf16 v[110:113], v[154:157], v[202:205], v[110:113]
	v_mfma_f32_16x16x32_bf16 v[106:109], v[162:165], v[202:205], v[106:109]
	v_mfma_f32_16x16x32_bf16 v[94:97], v[154:157], v[210:213], v[94:97]
	v_mfma_f32_16x16x32_bf16 v[90:93], v[162:165], v[210:213], v[90:93]
	v_mfma_f32_16x16x32_bf16 v[78:81], v[154:157], v[218:221], v[78:81]
	v_mfma_f32_16x16x32_bf16 v[74:77], v[162:165], v[218:221], v[74:77]
	v_mfma_f32_16x16x32_bf16 v[118:121], v[166:169], v[182:185], v[118:121]
	v_mfma_f32_16x16x32_bf16 v[114:117], v[174:177], v[182:185], v[114:117]
	v_mfma_f32_16x16x32_bf16 v[102:105], v[166:169], v[190:193], v[102:105]
	v_mfma_f32_16x16x32_bf16 v[98:101], v[174:177], v[190:193], v[98:101]
	v_mfma_f32_16x16x32_bf16 v[86:89], v[166:169], v[206:209], v[86:89]
	v_mfma_f32_16x16x32_bf16 v[82:85], v[174:177], v[206:209], v[82:85]
	v_mfma_f32_16x16x32_bf16 v[70:73], v[166:169], v[214:217], v[70:73]
	v_mfma_f32_16x16x32_bf16 v[66:69], v[174:177], v[214:217], v[66:69]
	v_mfma_f32_16x16x32_bf16 v[118:121], v[170:173], v[186:189], v[118:121]
	v_mfma_f32_16x16x32_bf16 v[114:117], v[178:181], v[186:189], v[114:117]
	v_mfma_f32_16x16x32_bf16 v[102:105], v[170:173], v[202:205], v[102:105]
	v_mfma_f32_16x16x32_bf16 v[98:101], v[178:181], v[202:205], v[98:101]
	v_mfma_f32_16x16x32_bf16 v[86:89], v[170:173], v[210:213], v[86:89]
	v_mfma_f32_16x16x32_bf16 v[82:85], v[178:181], v[210:213], v[82:85]
	v_mfma_f32_16x16x32_bf16 v[70:73], v[170:173], v[218:221], v[70:73]
	v_mfma_f32_16x16x32_bf16 v[66:69], v[178:181], v[218:221], v[66:69]
	s_barrier
	s_setprio 0
	s_add_i32 s85, s85, s44
	v_lshl_add_u64 v[194:195], s[36:37], 0, v[134:135]
	s_mov_b32 m0, s85
	ds_read_b128 v[182:185], v153 offset:16384
	ds_read_b128 v[186:189], v153 offset:17408
	ds_read_b128 v[190:193], v153 offset:18432
	ds_read_b128 v[202:205], v153 offset:19456
	ds_read_b128 v[206:209], v153 offset:20480
	ds_read_b128 v[210:213], v153 offset:21504
	ds_read_b128 v[214:217], v153 offset:22528
	ds_read_b128 v[218:221], v153 offset:23552
	s_mov_b64 exec, s[98:99]
	global_load_lds_dwordx4 v[194:195], off
	s_add_i32 m0, s85, 0x2000
	s_add_u32 s86, s36, 0x40000
	v_lshl_add_u64 v[198:199], s[36:37], 0, v[130:131]
	s_addc_u32 s87, s37, 0
	s_add_i32 s85, vcc_lo, s44
	global_load_lds_dwordx4 v[198:199], off
	v_lshl_add_u64 v[222:223], s[86:87], 0, v[134:135]
	s_mov_b32 m0, s85
	s_nop 0
	global_load_lds_dwordx4 v[222:223], off
	v_lshl_add_u64 v[222:223], s[86:87], 0, v[130:131]
	s_add_i32 m0, s85, 0x2000
	s_nop 0
	global_load_lds_dwordx4 v[222:223], off
	v_lshl_add_u64 v[222:223], s[38:39], 0, v[136:137]
	s_mov_b32 m0, s45
	s_nop 0
	global_load_lds_dwordx4 v[222:223], off
	v_lshl_add_u64 v[222:223], s[38:39], 0, v[132:133]
	s_mov_b32 m0, s51
	s_nop 0
	global_load_lds_dwordx4 v[222:223], off
	s_mov_b64 exec, -1
	s_waitcnt vmcnt(8)
	s_waitcnt lgkmcnt(0)
	s_setprio 1
	s_barrier
	v_mfma_f32_16x16x32_bf16 v[62:65], v[148:151], v[182:185], v[62:65]
	v_mfma_f32_16x16x32_bf16 v[58:61], v[158:161], v[182:185], v[58:61]
	v_mfma_f32_16x16x32_bf16 v[46:49], v[148:151], v[190:193], v[46:49]
	v_mfma_f32_16x16x32_bf16 v[42:45], v[158:161], v[190:193], v[42:45]
	v_mfma_f32_16x16x32_bf16 v[30:33], v[148:151], v[206:209], v[30:33]
	v_mfma_f32_16x16x32_bf16 v[26:29], v[158:161], v[206:209], v[26:29]
	v_mfma_f32_16x16x32_bf16 v[14:17], v[148:151], v[214:217], v[14:17]
	v_mfma_f32_16x16x32_bf16 v[10:13], v[158:161], v[214:217], v[10:13]
	v_mfma_f32_16x16x32_bf16 v[62:65], v[154:157], v[186:189], v[62:65]
	v_mfma_f32_16x16x32_bf16 v[58:61], v[162:165], v[186:189], v[58:61]
	v_mfma_f32_16x16x32_bf16 v[46:49], v[154:157], v[202:205], v[46:49]
	v_mfma_f32_16x16x32_bf16 v[42:45], v[162:165], v[202:205], v[42:45]
	v_mfma_f32_16x16x32_bf16 v[30:33], v[154:157], v[210:213], v[30:33]
	v_mfma_f32_16x16x32_bf16 v[26:29], v[162:165], v[210:213], v[26:29]
	v_mfma_f32_16x16x32_bf16 v[14:17], v[154:157], v[218:221], v[14:17]
	v_mfma_f32_16x16x32_bf16 v[10:13], v[162:165], v[218:221], v[10:13]
	v_mfma_f32_16x16x32_bf16 v[54:57], v[166:169], v[182:185], v[54:57]
	v_mfma_f32_16x16x32_bf16 v[50:53], v[174:177], v[182:185], v[50:53]
	v_mfma_f32_16x16x32_bf16 v[38:41], v[166:169], v[190:193], v[38:41]
	v_mfma_f32_16x16x32_bf16 v[34:37], v[174:177], v[190:193], v[34:37]
	v_mfma_f32_16x16x32_bf16 v[22:25], v[166:169], v[206:209], v[22:25]
	v_mfma_f32_16x16x32_bf16 v[18:21], v[174:177], v[206:209], v[18:21]
	v_mfma_f32_16x16x32_bf16 v[6:9], v[166:169], v[214:217], v[6:9]
	v_mfma_f32_16x16x32_bf16 v[2:5], v[174:177], v[214:217], v[2:5]
	v_mfma_f32_16x16x32_bf16 v[54:57], v[170:173], v[186:189], v[54:57]
	v_mfma_f32_16x16x32_bf16 v[50:53], v[178:181], v[186:189], v[50:53]
	v_mfma_f32_16x16x32_bf16 v[38:41], v[170:173], v[202:205], v[38:41]
	v_mfma_f32_16x16x32_bf16 v[34:37], v[178:181], v[202:205], v[34:37]
	v_mfma_f32_16x16x32_bf16 v[22:25], v[170:173], v[210:213], v[22:25]
	v_mfma_f32_16x16x32_bf16 v[18:21], v[178:181], v[210:213], v[18:21]
	v_mfma_f32_16x16x32_bf16 v[6:9], v[170:173], v[218:221], v[6:9]
	v_mfma_f32_16x16x32_bf16 v[2:5], v[178:181], v[218:221], v[2:5]
	s_barrier
	s_setprio 0
	s_add_i32 s85, 0, 0x18000
	v_add_u32_e32 v0, s85, v152
	s_add_i32 s86, 0, 0x1c000
	ds_read_b128 v[148:151], v0
	ds_read_b128 v[154:157], v0 offset:1024
	ds_read_b128 v[158:161], v0 offset:2048
	ds_read_b128 v[162:165], v0 offset:3072
	v_add_u32_e32 v0, s86, v152
	ds_read_b128 v[166:169], v0
	ds_read_b128 v[170:173], v0 offset:1024
	ds_read_b128 v[174:177], v0 offset:2048
	ds_read_b128 v[178:181], v0 offset:3072
	s_add_u32 s38, s38, 0x40000
	s_addc_u32 s39, s39, 0
	s_mov_b32 m0, s55
	v_lshl_add_u64 v[222:223], s[38:39], 0, v[136:137]
	ds_read_b128 v[182:185], v153 offset:32768
	ds_read_b128 v[186:189], v153 offset:33792
	ds_read_b128 v[190:193], v153 offset:34816
	ds_read_b128 v[202:205], v153 offset:35840
	ds_read_b128 v[206:209], v153 offset:36864
	ds_read_b128 v[210:213], v153 offset:37888
	ds_read_b128 v[214:217], v153 offset:38912
	ds_read_b128 v[218:221], v153 offset:39936
	s_mov_b64 exec, s[98:99]
	global_load_lds_dwordx4 v[222:223], off
	v_lshl_add_u64 v[222:223], s[38:39], 0, v[132:133]
	s_mov_b32 m0, s56
	s_nop 0
	global_load_lds_dwordx4 v[222:223], off
	s_mov_b64 exec, -1
	s_waitcnt vmcnt(8)
	s_waitcnt lgkmcnt(0)
	s_setprio 1
	s_barrier
	v_mfma_f32_16x16x32_bf16 v[126:129], v[148:151], v[182:185], v[126:129]
	v_mfma_f32_16x16x32_bf16 v[122:125], v[158:161], v[182:185], v[122:125]
	v_mfma_f32_16x16x32_bf16 v[110:113], v[148:151], v[190:193], v[110:113]
	v_mfma_f32_16x16x32_bf16 v[106:109], v[158:161], v[190:193], v[106:109]
	v_mfma_f32_16x16x32_bf16 v[94:97], v[148:151], v[206:209], v[94:97]
	v_mfma_f32_16x16x32_bf16 v[90:93], v[158:161], v[206:209], v[90:93]
	v_mfma_f32_16x16x32_bf16 v[78:81], v[148:151], v[214:217], v[78:81]
	v_mfma_f32_16x16x32_bf16 v[74:77], v[158:161], v[214:217], v[74:77]
	v_mfma_f32_16x16x32_bf16 v[126:129], v[154:157], v[186:189], v[126:129]
	v_mfma_f32_16x16x32_bf16 v[122:125], v[162:165], v[186:189], v[122:125]
	v_mfma_f32_16x16x32_bf16 v[110:113], v[154:157], v[202:205], v[110:113]
	v_mfma_f32_16x16x32_bf16 v[106:109], v[162:165], v[202:205], v[106:109]
	v_mfma_f32_16x16x32_bf16 v[94:97], v[154:157], v[210:213], v[94:97]
	v_mfma_f32_16x16x32_bf16 v[90:93], v[162:165], v[210:213], v[90:93]
	v_mfma_f32_16x16x32_bf16 v[78:81], v[154:157], v[218:221], v[78:81]
	v_mfma_f32_16x16x32_bf16 v[74:77], v[162:165], v[218:221], v[74:77]
	v_mfma_f32_16x16x32_bf16 v[118:121], v[166:169], v[182:185], v[118:121]
	v_mfma_f32_16x16x32_bf16 v[114:117], v[174:177], v[182:185], v[114:117]
	v_mfma_f32_16x16x32_bf16 v[102:105], v[166:169], v[190:193], v[102:105]
	v_mfma_f32_16x16x32_bf16 v[98:101], v[174:177], v[190:193], v[98:101]
	v_mfma_f32_16x16x32_bf16 v[86:89], v[166:169], v[206:209], v[86:89]
	v_mfma_f32_16x16x32_bf16 v[82:85], v[174:177], v[206:209], v[82:85]
	v_mfma_f32_16x16x32_bf16 v[70:73], v[166:169], v[214:217], v[70:73]
	v_mfma_f32_16x16x32_bf16 v[66:69], v[174:177], v[214:217], v[66:69]
	v_mfma_f32_16x16x32_bf16 v[118:121], v[170:173], v[186:189], v[118:121]
	v_mfma_f32_16x16x32_bf16 v[114:117], v[178:181], v[186:189], v[114:117]
	v_mfma_f32_16x16x32_bf16 v[102:105], v[170:173], v[202:205], v[102:105]
	v_mfma_f32_16x16x32_bf16 v[98:101], v[178:181], v[202:205], v[98:101]
	v_mfma_f32_16x16x32_bf16 v[86:89], v[170:173], v[210:213], v[86:89]
	v_mfma_f32_16x16x32_bf16 v[82:85], v[178:181], v[210:213], v[82:85]
	v_mfma_f32_16x16x32_bf16 v[70:73], v[170:173], v[218:221], v[70:73]
	v_mfma_f32_16x16x32_bf16 v[66:69], v[178:181], v[218:221], v[66:69]
	s_barrier
	s_setprio 0
	s_add_i32 s38, s85, s44
	v_lshl_add_u64 v[194:195], v[194:195], 0, s[90:91]
	s_mov_b32 m0, s38
	ds_read_b128 v[182:185], v153 offset:49152
	ds_read_b128 v[186:189], v153 offset:50176
	ds_read_b128 v[190:193], v153 offset:51200
	ds_read_b128 v[202:205], v153 offset:52224
	ds_read_b128 v[206:209], v153 offset:53248
	ds_read_b128 v[210:213], v153 offset:54272
	ds_read_b128 v[214:217], v153 offset:55296
	ds_read_b128 v[218:221], v153 offset:56320
	s_mov_b64 exec, s[98:99]
	global_load_lds_dwordx4 v[194:195], off
	s_add_i32 m0, s38, 0x2000
	s_add_u32 s36, s36, 0x40080
	v_lshl_add_u64 v[194:195], v[198:199], 0, s[90:91]
	s_addc_u32 s37, s37, 0
	s_add_i32 s38, s86, s44
	global_load_lds_dwordx4 v[194:195], off
	v_lshl_add_u64 v[194:195], s[36:37], 0, v[134:135]
	s_mov_b32 m0, s38
	s_nop 0
	global_load_lds_dwordx4 v[194:195], off
	v_lshl_add_u64 v[194:195], s[36:37], 0, v[130:131]
	s_add_i32 m0, s38, 0x2000
	s_nop 0
	global_load_lds_dwordx4 v[194:195], off
	v_lshl_add_u64 v[194:195], s[34:35], 0, v[136:137]
	s_mov_b32 m0, s58
	s_nop 0
	global_load_lds_dwordx4 v[194:195], off
	v_lshl_add_u64 v[194:195], s[34:35], 0, v[132:133]
	s_mov_b32 m0, s59
	s_nop 0
	global_load_lds_dwordx4 v[194:195], off
	s_mov_b64 exec, -1
	s_waitcnt vmcnt(8)
	s_waitcnt lgkmcnt(0)
	s_setprio 1
	s_barrier
	v_mfma_f32_16x16x32_bf16 v[62:65], v[148:151], v[182:185], v[62:65]
	v_mfma_f32_16x16x32_bf16 v[58:61], v[158:161], v[182:185], v[58:61]
	v_mfma_f32_16x16x32_bf16 v[46:49], v[148:151], v[190:193], v[46:49]
	v_mfma_f32_16x16x32_bf16 v[42:45], v[158:161], v[190:193], v[42:45]
	v_mfma_f32_16x16x32_bf16 v[30:33], v[148:151], v[206:209], v[30:33]
	v_mfma_f32_16x16x32_bf16 v[26:29], v[158:161], v[206:209], v[26:29]
	v_mfma_f32_16x16x32_bf16 v[14:17], v[148:151], v[214:217], v[14:17]
	v_mfma_f32_16x16x32_bf16 v[10:13], v[158:161], v[214:217], v[10:13]
	v_mfma_f32_16x16x32_bf16 v[62:65], v[154:157], v[186:189], v[62:65]
	v_mfma_f32_16x16x32_bf16 v[58:61], v[162:165], v[186:189], v[58:61]
	v_mfma_f32_16x16x32_bf16 v[46:49], v[154:157], v[202:205], v[46:49]
	v_mfma_f32_16x16x32_bf16 v[42:45], v[162:165], v[202:205], v[42:45]
	v_mfma_f32_16x16x32_bf16 v[30:33], v[154:157], v[210:213], v[30:33]
	v_mfma_f32_16x16x32_bf16 v[26:29], v[162:165], v[210:213], v[26:29]
	v_mfma_f32_16x16x32_bf16 v[14:17], v[154:157], v[218:221], v[14:17]
	v_mfma_f32_16x16x32_bf16 v[10:13], v[162:165], v[218:221], v[10:13]
	v_mfma_f32_16x16x32_bf16 v[54:57], v[166:169], v[182:185], v[54:57]
	v_mfma_f32_16x16x32_bf16 v[50:53], v[174:177], v[182:185], v[50:53]
	v_mfma_f32_16x16x32_bf16 v[38:41], v[166:169], v[190:193], v[38:41]
	v_mfma_f32_16x16x32_bf16 v[34:37], v[174:177], v[190:193], v[34:37]
	v_mfma_f32_16x16x32_bf16 v[22:25], v[166:169], v[206:209], v[22:25]
	v_mfma_f32_16x16x32_bf16 v[18:21], v[174:177], v[206:209], v[18:21]
	v_mfma_f32_16x16x32_bf16 v[6:9], v[166:169], v[214:217], v[6:9]
	v_mfma_f32_16x16x32_bf16 v[2:5], v[174:177], v[214:217], v[2:5]
	v_mfma_f32_16x16x32_bf16 v[54:57], v[170:173], v[186:189], v[54:57]
	v_mfma_f32_16x16x32_bf16 v[50:53], v[178:181], v[186:189], v[50:53]
	v_mfma_f32_16x16x32_bf16 v[38:41], v[170:173], v[202:205], v[38:41]
	v_mfma_f32_16x16x32_bf16 v[34:37], v[178:181], v[202:205], v[34:37]
	v_mfma_f32_16x16x32_bf16 v[22:25], v[170:173], v[210:213], v[22:25]
	v_mfma_f32_16x16x32_bf16 v[18:21], v[178:181], v[210:213], v[18:21]
	v_mfma_f32_16x16x32_bf16 v[6:9], v[170:173], v[218:221], v[6:9]
	v_mfma_f32_16x16x32_bf16 v[2:5], v[178:181], v[218:221], v[2:5]
	s_barrier
	s_setprio 0
	s_add_i32 s78, s78, 2
	s_add_u32 s30, s30, 0x100
	s_addc_u32 s31, s31, 0
	s_cmp_gt_u32 s78, 13
	s_cbranch_scc0 .LBB0_345

.LBB0_675:
	s_add_u32 s4, s30, s34
	s_addc_u32 s5, s31, s35
	s_add_u32 s40, s4, 0x100
	s_addc_u32 s41, s5, 0
	s_add_u32 s38, s78, s34
	s_addc_u32 s39, s85, s35
	s_add_u32 s4, s4, 0x180
	s_addc_u32 s5, s5, 0
	s_add_i32 s87, 0, 0x10000
	s_add_i32 s65, 0, 0x14000
	v_add_u32_e32 v0, s87, v148
	ds_read_b128 v[150:153], v0
	ds_read_b128 v[154:157], v0 offset:1024
	ds_read_b128 v[158:161], v0 offset:2048
	ds_read_b128 v[162:165], v0 offset:3072
	v_add_u32_e32 v0, s65, v148
	ds_read_b128 v[166:169], v0
	ds_read_b128 v[170:173], v0 offset:1024
	ds_read_b128 v[174:177], v0 offset:2048
	ds_read_b128 v[178:181], v0 offset:3072
	s_cmpk_eq_i32 s34, 0x700
	s_cselect_b64 s[98:99], s[10:11], -1
	s_cselect_b32 s37, s76, s5
	s_cselect_b32 s36, s75, s4
	s_cselect_b32 s39, s23, s39
	s_cselect_b32 s38, s74, s38
	s_cselect_b32 s41, s25, s41
	s_cselect_b32 s40, s73, s40
	v_lshl_add_u64 v[194:195], v[144:145], 0, s[34:35]
	s_add_i32 m0, s55, 0xc000
	ds_read_b128 v[182:185], v149
	ds_read_b128 v[186:189], v149 offset:1024
	ds_read_b128 v[190:193], v149 offset:2048
	ds_read_b128 v[202:205], v149 offset:3072
	ds_read_b128 v[206:209], v149 offset:4096
	ds_read_b128 v[210:213], v149 offset:5120
	ds_read_b128 v[214:217], v149 offset:6144
	ds_read_b128 v[218:221], v149 offset:7168
	global_load_lds_dwordx4 v[194:195], off
	v_lshl_add_u64 v[194:195], v[146:147], 0, s[34:35]
	s_add_i32 m0, s55, 0xe000
	s_nop 0
	global_load_lds_dwordx4 v[194:195], off
	s_waitcnt vmcnt(8)
	s_waitcnt lgkmcnt(0)
	s_setprio 1
	s_barrier
	v_mfma_f32_16x16x32_bf16 v[126:129], v[150:153], v[182:185], v[126:129]
	v_mfma_f32_16x16x32_bf16 v[122:125], v[158:161], v[182:185], v[122:125]
	v_mfma_f32_16x16x32_bf16 v[110:113], v[150:153], v[190:193], v[110:113]
	v_mfma_f32_16x16x32_bf16 v[106:109], v[158:161], v[190:193], v[106:109]
	v_mfma_f32_16x16x32_bf16 v[94:97], v[150:153], v[206:209], v[94:97]
	v_mfma_f32_16x16x32_bf16 v[90:93], v[158:161], v[206:209], v[90:93]
	v_mfma_f32_16x16x32_bf16 v[78:81], v[150:153], v[214:217], v[78:81]
	v_mfma_f32_16x16x32_bf16 v[74:77], v[158:161], v[214:217], v[74:77]
	v_mfma_f32_16x16x32_bf16 v[126:129], v[154:157], v[186:189], v[126:129]
	v_mfma_f32_16x16x32_bf16 v[122:125], v[162:165], v[186:189], v[122:125]
	v_mfma_f32_16x16x32_bf16 v[110:113], v[154:157], v[202:205], v[110:113]
	v_mfma_f32_16x16x32_bf16 v[106:109], v[162:165], v[202:205], v[106:109]
	v_mfma_f32_16x16x32_bf16 v[94:97], v[154:157], v[210:213], v[94:97]
	v_mfma_f32_16x16x32_bf16 v[90:93], v[162:165], v[210:213], v[90:93]
	v_mfma_f32_16x16x32_bf16 v[78:81], v[154:157], v[218:221], v[78:81]
	v_mfma_f32_16x16x32_bf16 v[74:77], v[162:165], v[218:221], v[74:77]
	v_mfma_f32_16x16x32_bf16 v[118:121], v[166:169], v[182:185], v[118:121]
	v_mfma_f32_16x16x32_bf16 v[114:117], v[174:177], v[182:185], v[114:117]
	v_mfma_f32_16x16x32_bf16 v[102:105], v[166:169], v[190:193], v[102:105]
	v_mfma_f32_16x16x32_bf16 v[98:101], v[174:177], v[190:193], v[98:101]
	v_mfma_f32_16x16x32_bf16 v[86:89], v[166:169], v[206:209], v[86:89]
	v_mfma_f32_16x16x32_bf16 v[82:85], v[174:177], v[206:209], v[82:85]
	v_mfma_f32_16x16x32_bf16 v[70:73], v[166:169], v[214:217], v[70:73]
	v_mfma_f32_16x16x32_bf16 v[66:69], v[174:177], v[214:217], v[66:69]
	v_mfma_f32_16x16x32_bf16 v[118:121], v[170:173], v[186:189], v[118:121]
	v_mfma_f32_16x16x32_bf16 v[114:117], v[178:181], v[186:189], v[114:117]
	v_mfma_f32_16x16x32_bf16 v[102:105], v[170:173], v[202:205], v[102:105]
	v_mfma_f32_16x16x32_bf16 v[98:101], v[178:181], v[202:205], v[98:101]
	v_mfma_f32_16x16x32_bf16 v[86:89], v[170:173], v[210:213], v[86:89]
	v_mfma_f32_16x16x32_bf16 v[82:85], v[178:181], v[210:213], v[82:85]
	v_mfma_f32_16x16x32_bf16 v[70:73], v[170:173], v[218:221], v[70:73]
	v_mfma_f32_16x16x32_bf16 v[66:69], v[178:181], v[218:221], v[66:69]
	s_barrier
	s_setprio 0
	s_add_i32 s4, s87, s51
	v_lshl_add_u64 v[194:195], s[38:39], 0, v[134:135]
	s_mov_b32 m0, s4
	ds_read_b128 v[182:185], v149 offset:16384
	ds_read_b128 v[186:189], v149 offset:17408
	ds_read_b128 v[190:193], v149 offset:18432
	ds_read_b128 v[202:205], v149 offset:19456
	ds_read_b128 v[206:209], v149 offset:20480
	ds_read_b128 v[210:213], v149 offset:21504
	ds_read_b128 v[214:217], v149 offset:22528
	ds_read_b128 v[218:221], v149 offset:23552
	s_mov_b64 exec, s[98:99]
	global_load_lds_dwordx4 v[194:195], off
	s_add_i32 m0, s4, 0x2000
	s_add_u32 vcc_lo, s38, 0x40000
	v_lshl_add_u64 v[198:199], s[38:39], 0, v[130:131]
	s_addc_u32 vcc_hi, s39, 0
	s_add_i32 s4, s65, s51
	global_load_lds_dwordx4 v[198:199], off
	v_lshl_add_u64 v[222:223], vcc, 0, v[134:135]
	s_mov_b32 m0, s4
	s_nop 0
	global_load_lds_dwordx4 v[222:223], off
	v_lshl_add_u64 v[222:223], vcc, 0, v[130:131]
	s_add_i32 m0, s4, 0x2000
	s_nop 0
	global_load_lds_dwordx4 v[222:223], off
	v_lshl_add_u64 v[222:223], s[40:41], 0, v[136:137]
	s_mov_b32 m0, s55
	s_nop 0
	global_load_lds_dwordx4 v[222:223], off
	v_lshl_add_u64 v[222:223], s[40:41], 0, v[132:133]
	s_mov_b32 m0, s56
	s_nop 0
	global_load_lds_dwordx4 v[222:223], off
	s_mov_b64 exec, -1
	s_waitcnt vmcnt(8)
	s_waitcnt lgkmcnt(0)
	s_setprio 1
	s_barrier
	v_mfma_f32_16x16x32_bf16 v[62:65], v[150:153], v[182:185], v[62:65]
	v_mfma_f32_16x16x32_bf16 v[58:61], v[158:161], v[182:185], v[58:61]
	v_mfma_f32_16x16x32_bf16 v[46:49], v[150:153], v[190:193], v[46:49]
	v_mfma_f32_16x16x32_bf16 v[42:45], v[158:161], v[190:193], v[42:45]
	v_mfma_f32_16x16x32_bf16 v[30:33], v[150:153], v[206:209], v[30:33]
	v_mfma_f32_16x16x32_bf16 v[26:29], v[158:161], v[206:209], v[26:29]
	v_mfma_f32_16x16x32_bf16 v[14:17], v[150:153], v[214:217], v[14:17]
	v_mfma_f32_16x16x32_bf16 v[10:13], v[158:161], v[214:217], v[10:13]
	v_mfma_f32_16x16x32_bf16 v[62:65], v[154:157], v[186:189], v[62:65]
	v_mfma_f32_16x16x32_bf16 v[58:61], v[162:165], v[186:189], v[58:61]
	v_mfma_f32_16x16x32_bf16 v[46:49], v[154:157], v[202:205], v[46:49]
	v_mfma_f32_16x16x32_bf16 v[42:45], v[162:165], v[202:205], v[42:45]
	v_mfma_f32_16x16x32_bf16 v[30:33], v[154:157], v[210:213], v[30:33]
	v_mfma_f32_16x16x32_bf16 v[26:29], v[162:165], v[210:213], v[26:29]
	v_mfma_f32_16x16x32_bf16 v[14:17], v[154:157], v[218:221], v[14:17]
	v_mfma_f32_16x16x32_bf16 v[10:13], v[162:165], v[218:221], v[10:13]
	v_mfma_f32_16x16x32_bf16 v[54:57], v[166:169], v[182:185], v[54:57]
	v_mfma_f32_16x16x32_bf16 v[50:53], v[174:177], v[182:185], v[50:53]
	v_mfma_f32_16x16x32_bf16 v[38:41], v[166:169], v[190:193], v[38:41]
	v_mfma_f32_16x16x32_bf16 v[34:37], v[174:177], v[190:193], v[34:37]
	v_mfma_f32_16x16x32_bf16 v[22:25], v[166:169], v[206:209], v[22:25]
	v_mfma_f32_16x16x32_bf16 v[18:21], v[174:177], v[206:209], v[18:21]
	v_mfma_f32_16x16x32_bf16 v[6:9], v[166:169], v[214:217], v[6:9]
	v_mfma_f32_16x16x32_bf16 v[2:5], v[174:177], v[214:217], v[2:5]
	v_mfma_f32_16x16x32_bf16 v[54:57], v[170:173], v[186:189], v[54:57]
	v_mfma_f32_16x16x32_bf16 v[50:53], v[178:181], v[186:189], v[50:53]
	v_mfma_f32_16x16x32_bf16 v[38:41], v[170:173], v[202:205], v[38:41]
	v_mfma_f32_16x16x32_bf16 v[34:37], v[178:181], v[202:205], v[34:37]
	v_mfma_f32_16x16x32_bf16 v[22:25], v[170:173], v[210:213], v[22:25]
	v_mfma_f32_16x16x32_bf16 v[18:21], v[178:181], v[210:213], v[18:21]
	v_mfma_f32_16x16x32_bf16 v[6:9], v[170:173], v[218:221], v[6:9]
	v_mfma_f32_16x16x32_bf16 v[2:5], v[178:181], v[218:221], v[2:5]
	s_barrier
	s_setprio 0
	s_add_i32 s4, 0, 0x18000
	v_add_u32_e32 v0, s4, v148
	s_add_i32 s5, 0, 0x1c000
	ds_read_b128 v[150:153], v0
	ds_read_b128 v[154:157], v0 offset:1024
	ds_read_b128 v[158:161], v0 offset:2048
	ds_read_b128 v[162:165], v0 offset:3072
	v_add_u32_e32 v0, s5, v148
	ds_read_b128 v[166:169], v0
	ds_read_b128 v[170:173], v0 offset:1024
	ds_read_b128 v[174:177], v0 offset:2048
	ds_read_b128 v[178:181], v0 offset:3072
	s_add_u32 s40, s40, 0x40000
	s_addc_u32 s41, s41, 0
	s_mov_b32 m0, s57
	v_lshl_add_u64 v[222:223], s[40:41], 0, v[136:137]
	ds_read_b128 v[182:185], v149 offset:32768
	ds_read_b128 v[186:189], v149 offset:33792
	ds_read_b128 v[190:193], v149 offset:34816
	ds_read_b128 v[202:205], v149 offset:35840
	ds_read_b128 v[206:209], v149 offset:36864
	ds_read_b128 v[210:213], v149 offset:37888
	ds_read_b128 v[214:217], v149 offset:38912
	ds_read_b128 v[218:221], v149 offset:39936
	s_mov_b64 exec, s[98:99]
	global_load_lds_dwordx4 v[222:223], off
	v_lshl_add_u64 v[222:223], s[40:41], 0, v[132:133]
	s_mov_b32 m0, s58
	s_nop 0
	global_load_lds_dwordx4 v[222:223], off
	s_mov_b64 exec, -1
	s_waitcnt vmcnt(8)
	s_waitcnt lgkmcnt(0)
	s_setprio 1
	s_barrier
	v_mfma_f32_16x16x32_bf16 v[126:129], v[150:153], v[182:185], v[126:129]
	v_mfma_f32_16x16x32_bf16 v[122:125], v[158:161], v[182:185], v[122:125]
	v_mfma_f32_16x16x32_bf16 v[110:113], v[150:153], v[190:193], v[110:113]
	v_mfma_f32_16x16x32_bf16 v[106:109], v[158:161], v[190:193], v[106:109]
	v_mfma_f32_16x16x32_bf16 v[94:97], v[150:153], v[206:209], v[94:97]
	v_mfma_f32_16x16x32_bf16 v[90:93], v[158:161], v[206:209], v[90:93]
	v_mfma_f32_16x16x32_bf16 v[78:81], v[150:153], v[214:217], v[78:81]
	v_mfma_f32_16x16x32_bf16 v[74:77], v[158:161], v[214:217], v[74:77]
	v_mfma_f32_16x16x32_bf16 v[126:129], v[154:157], v[186:189], v[126:129]
	v_mfma_f32_16x16x32_bf16 v[122:125], v[162:165], v[186:189], v[122:125]
	v_mfma_f32_16x16x32_bf16 v[110:113], v[154:157], v[202:205], v[110:113]
	v_mfma_f32_16x16x32_bf16 v[106:109], v[162:165], v[202:205], v[106:109]
	v_mfma_f32_16x16x32_bf16 v[94:97], v[154:157], v[210:213], v[94:97]
	v_mfma_f32_16x16x32_bf16 v[90:93], v[162:165], v[210:213], v[90:93]
	v_mfma_f32_16x16x32_bf16 v[78:81], v[154:157], v[218:221], v[78:81]
	v_mfma_f32_16x16x32_bf16 v[74:77], v[162:165], v[218:221], v[74:77]
	v_mfma_f32_16x16x32_bf16 v[118:121], v[166:169], v[182:185], v[118:121]
	v_mfma_f32_16x16x32_bf16 v[114:117], v[174:177], v[182:185], v[114:117]
	v_mfma_f32_16x16x32_bf16 v[102:105], v[166:169], v[190:193], v[102:105]
	v_mfma_f32_16x16x32_bf16 v[98:101], v[174:177], v[190:193], v[98:101]
	v_mfma_f32_16x16x32_bf16 v[86:89], v[166:169], v[206:209], v[86:89]
	v_mfma_f32_16x16x32_bf16 v[82:85], v[174:177], v[206:209], v[82:85]
	v_mfma_f32_16x16x32_bf16 v[70:73], v[166:169], v[214:217], v[70:73]
	v_mfma_f32_16x16x32_bf16 v[66:69], v[174:177], v[214:217], v[66:69]
	v_mfma_f32_16x16x32_bf16 v[118:121], v[170:173], v[186:189], v[118:121]
	v_mfma_f32_16x16x32_bf16 v[114:117], v[178:181], v[186:189], v[114:117]
	v_mfma_f32_16x16x32_bf16 v[102:105], v[170:173], v[202:205], v[102:105]
	v_mfma_f32_16x16x32_bf16 v[98:101], v[178:181], v[202:205], v[98:101]
	v_mfma_f32_16x16x32_bf16 v[86:89], v[170:173], v[210:213], v[86:89]
	v_mfma_f32_16x16x32_bf16 v[82:85], v[178:181], v[210:213], v[82:85]
	v_mfma_f32_16x16x32_bf16 v[70:73], v[170:173], v[218:221], v[70:73]
	v_mfma_f32_16x16x32_bf16 v[66:69], v[178:181], v[218:221], v[66:69]
	s_barrier
	s_setprio 0
	s_add_i32 s4, s4, s51
	v_lshl_add_u64 v[194:195], v[194:195], 0, s[90:91]
	s_mov_b32 m0, s4
	ds_read_b128 v[182:185], v149 offset:49152
	ds_read_b128 v[186:189], v149 offset:50176
	ds_read_b128 v[190:193], v149 offset:51200
	ds_read_b128 v[202:205], v149 offset:52224
	ds_read_b128 v[206:209], v149 offset:53248
	ds_read_b128 v[210:213], v149 offset:54272
	ds_read_b128 v[214:217], v149 offset:55296
	ds_read_b128 v[218:221], v149 offset:56320
	s_mov_b64 exec, s[98:99]
	global_load_lds_dwordx4 v[194:195], off
	s_add_i32 m0, s4, 0x2000
	s_add_u32 s38, s38, 0x40080
	v_lshl_add_u64 v[194:195], v[198:199], 0, s[90:91]
	s_addc_u32 s39, s39, 0
	s_add_i32 s4, s5, s51
	global_load_lds_dwordx4 v[194:195], off
	v_lshl_add_u64 v[194:195], s[38:39], 0, v[134:135]
	s_mov_b32 m0, s4
	s_nop 0
	global_load_lds_dwordx4 v[194:195], off
	v_lshl_add_u64 v[194:195], s[38:39], 0, v[130:131]
	s_add_i32 m0, s4, 0x2000
	s_nop 0
	global_load_lds_dwordx4 v[194:195], off
	v_lshl_add_u64 v[194:195], s[36:37], 0, v[136:137]
	s_mov_b32 m0, s68
	s_nop 0
	global_load_lds_dwordx4 v[194:195], off
	v_lshl_add_u64 v[194:195], s[36:37], 0, v[132:133]
	s_mov_b32 m0, s69
	s_nop 0
	global_load_lds_dwordx4 v[194:195], off
	s_mov_b64 exec, -1
	s_waitcnt vmcnt(8)
	s_waitcnt lgkmcnt(0)
	s_setprio 1
	s_barrier
	v_mfma_f32_16x16x32_bf16 v[62:65], v[150:153], v[182:185], v[62:65]
	v_mfma_f32_16x16x32_bf16 v[58:61], v[158:161], v[182:185], v[58:61]
	v_mfma_f32_16x16x32_bf16 v[46:49], v[150:153], v[190:193], v[46:49]
	v_mfma_f32_16x16x32_bf16 v[42:45], v[158:161], v[190:193], v[42:45]
	v_mfma_f32_16x16x32_bf16 v[30:33], v[150:153], v[206:209], v[30:33]
	v_mfma_f32_16x16x32_bf16 v[26:29], v[158:161], v[206:209], v[26:29]
	v_mfma_f32_16x16x32_bf16 v[14:17], v[150:153], v[214:217], v[14:17]
	v_mfma_f32_16x16x32_bf16 v[10:13], v[158:161], v[214:217], v[10:13]
	v_mfma_f32_16x16x32_bf16 v[62:65], v[154:157], v[186:189], v[62:65]
	v_mfma_f32_16x16x32_bf16 v[58:61], v[162:165], v[186:189], v[58:61]
	v_mfma_f32_16x16x32_bf16 v[46:49], v[154:157], v[202:205], v[46:49]
	v_mfma_f32_16x16x32_bf16 v[42:45], v[162:165], v[202:205], v[42:45]
	v_mfma_f32_16x16x32_bf16 v[30:33], v[154:157], v[210:213], v[30:33]
	v_mfma_f32_16x16x32_bf16 v[26:29], v[162:165], v[210:213], v[26:29]
	v_mfma_f32_16x16x32_bf16 v[14:17], v[154:157], v[218:221], v[14:17]
	v_mfma_f32_16x16x32_bf16 v[10:13], v[162:165], v[218:221], v[10:13]
	v_mfma_f32_16x16x32_bf16 v[54:57], v[166:169], v[182:185], v[54:57]
	v_mfma_f32_16x16x32_bf16 v[50:53], v[174:177], v[182:185], v[50:53]
	v_mfma_f32_16x16x32_bf16 v[38:41], v[166:169], v[190:193], v[38:41]
	v_mfma_f32_16x16x32_bf16 v[34:37], v[174:177], v[190:193], v[34:37]
	v_mfma_f32_16x16x32_bf16 v[22:25], v[166:169], v[206:209], v[22:25]
	v_mfma_f32_16x16x32_bf16 v[18:21], v[174:177], v[206:209], v[18:21]
	v_mfma_f32_16x16x32_bf16 v[6:9], v[166:169], v[214:217], v[6:9]
	v_mfma_f32_16x16x32_bf16 v[2:5], v[174:177], v[214:217], v[2:5]
	v_mfma_f32_16x16x32_bf16 v[54:57], v[170:173], v[186:189], v[54:57]
	v_mfma_f32_16x16x32_bf16 v[50:53], v[178:181], v[186:189], v[50:53]
	v_mfma_f32_16x16x32_bf16 v[38:41], v[170:173], v[202:205], v[38:41]
	v_mfma_f32_16x16x32_bf16 v[34:37], v[178:181], v[202:205], v[34:37]
	v_mfma_f32_16x16x32_bf16 v[22:25], v[170:173], v[210:213], v[22:25]
	v_mfma_f32_16x16x32_bf16 v[18:21], v[178:181], v[210:213], v[18:21]
	v_mfma_f32_16x16x32_bf16 v[6:9], v[170:173], v[218:221], v[6:9]
	v_mfma_f32_16x16x32_bf16 v[2:5], v[178:181], v[218:221], v[2:5]
	s_barrier
	s_setprio 0
	s_add_i32 s86, s86, 2
	s_add_u32 s34, s34, 0x100
	s_addc_u32 s35, s35, 0
	s_cmp_gt_u32 s86, 13
	s_cbranch_scc0 .LBB0_675

.LBB0_773:
	s_add_u32 s4, s30, s34
	s_addc_u32 s5, s31, s35
	s_add_u32 s40, s4, 0x100
	s_addc_u32 s41, s5, 0
	s_add_u32 s38, s78, s34
	s_addc_u32 s39, s85, s35
	s_add_u32 s4, s4, 0x180
	s_addc_u32 s5, s5, 0
	s_add_i32 s65, 0, 0x10000
	s_add_i32 s87, 0, 0x14000
	v_add_u32_e32 v138, s65, v231
	v_add_u32_e32 v162, s87, v231
	ds_read_b128 v[126:129], v138
	ds_read_b128 v[130:133], v138 offset:1024
	ds_read_b128 v[134:137], v138 offset:2048
	ds_read_b128 v[138:141], v138 offset:3072
	ds_read_b128 v[142:145], v162
	ds_read_b128 v[146:149], v162 offset:1024
	ds_read_b128 v[158:161], v162 offset:2048
	ds_read_b128 v[162:165], v162 offset:3072
	s_cmpk_eq_i32 s34, 0x700
	s_cselect_b64 s[98:99], s[8:9], -1
	s_cselect_b32 s37, s76, s5
	s_cselect_b32 s36, s75, s4
	s_cselect_b32 s39, s23, s39
	s_cselect_b32 s38, s74, s38
	s_cselect_b32 s41, s25, s41
	s_cselect_b32 s40, s73, s40
	v_lshl_add_u64 v[194:195], v[118:119], 0, s[34:35]
	s_add_i32 m0, s56, 0xc000
	ds_read_b128 v[166:169], v242
	ds_read_b128 v[170:173], v242 offset:1024
	ds_read_b128 v[174:177], v242 offset:2048
	ds_read_b128 v[178:181], v242 offset:3072
	ds_read_b128 v[182:185], v242 offset:4096
	ds_read_b128 v[186:189], v242 offset:5120
	ds_read_b128 v[208:211], v242 offset:6144
	ds_read_b128 v[212:215], v242 offset:7168
	global_load_lds_dwordx4 v[194:195], off
	v_lshl_add_u64 v[194:195], v[120:121], 0, s[34:35]
	s_add_i32 m0, s56, 0xe000
	s_nop 0
	global_load_lds_dwordx4 v[194:195], off
	s_waitcnt vmcnt(8)
	s_waitcnt lgkmcnt(0)
	s_setprio 1
	s_barrier
	v_mfma_f32_16x16x32_bf16 v[154:157], v[126:129], v[166:169], v[154:157]
	v_mfma_f32_16x16x32_bf16 v[150:153], v[134:137], v[166:169], v[150:153]
	v_mfma_f32_16x16x32_bf16 v[110:113], v[126:129], v[174:177], v[110:113]
	v_mfma_f32_16x16x32_bf16 v[106:109], v[134:137], v[174:177], v[106:109]
	v_mfma_f32_16x16x32_bf16 v[94:97], v[126:129], v[182:185], v[94:97]
	v_mfma_f32_16x16x32_bf16 v[90:93], v[134:137], v[182:185], v[90:93]
	v_mfma_f32_16x16x32_bf16 v[78:81], v[126:129], v[208:211], v[78:81]
	v_mfma_f32_16x16x32_bf16 v[74:77], v[134:137], v[208:211], v[74:77]
	v_mfma_f32_16x16x32_bf16 v[154:157], v[130:133], v[170:173], v[154:157]
	v_mfma_f32_16x16x32_bf16 v[150:153], v[138:141], v[170:173], v[150:153]
	v_mfma_f32_16x16x32_bf16 v[110:113], v[130:133], v[178:181], v[110:113]
	v_mfma_f32_16x16x32_bf16 v[106:109], v[138:141], v[178:181], v[106:109]
	v_mfma_f32_16x16x32_bf16 v[94:97], v[130:133], v[186:189], v[94:97]
	v_mfma_f32_16x16x32_bf16 v[90:93], v[138:141], v[186:189], v[90:93]
	v_mfma_f32_16x16x32_bf16 v[78:81], v[130:133], v[212:215], v[78:81]
	v_mfma_f32_16x16x32_bf16 v[74:77], v[138:141], v[212:215], v[74:77]
	v_mfma_f32_16x16x32_bf16 v[122:125], v[142:145], v[166:169], v[122:125]
	v_mfma_f32_16x16x32_bf16 v[114:117], v[158:161], v[166:169], v[114:117]
	v_mfma_f32_16x16x32_bf16 v[102:105], v[142:145], v[174:177], v[102:105]
	v_mfma_f32_16x16x32_bf16 v[98:101], v[158:161], v[174:177], v[98:101]
	v_mfma_f32_16x16x32_bf16 v[86:89], v[142:145], v[182:185], v[86:89]
	v_mfma_f32_16x16x32_bf16 v[82:85], v[158:161], v[182:185], v[82:85]
	v_mfma_f32_16x16x32_bf16 v[70:73], v[142:145], v[208:211], v[70:73]
	v_mfma_f32_16x16x32_bf16 v[66:69], v[158:161], v[208:211], v[66:69]
	v_mfma_f32_16x16x32_bf16 v[122:125], v[146:149], v[170:173], v[122:125]
	v_mfma_f32_16x16x32_bf16 v[114:117], v[162:165], v[170:173], v[114:117]
	v_mfma_f32_16x16x32_bf16 v[102:105], v[146:149], v[178:181], v[102:105]
	v_mfma_f32_16x16x32_bf16 v[98:101], v[162:165], v[178:181], v[98:101]
	v_mfma_f32_16x16x32_bf16 v[86:89], v[146:149], v[186:189], v[86:89]
	v_mfma_f32_16x16x32_bf16 v[82:85], v[162:165], v[186:189], v[82:85]
	v_mfma_f32_16x16x32_bf16 v[70:73], v[146:149], v[212:215], v[70:73]
	v_mfma_f32_16x16x32_bf16 v[66:69], v[162:165], v[212:215], v[66:69]
	s_barrier
	s_setprio 0
	s_add_i32 s4, s65, s51
	v_lshl_add_u64 v[194:195], s[38:39], 0, v[0:1]
	s_mov_b32 m0, s4
	ds_read_b128 v[166:169], v242 offset:16384
	ds_read_b128 v[170:173], v242 offset:17408
	ds_read_b128 v[174:177], v242 offset:18432
	ds_read_b128 v[178:181], v242 offset:19456
	ds_read_b128 v[182:185], v242 offset:20480
	ds_read_b128 v[186:189], v242 offset:21504
	ds_read_b128 v[208:211], v242 offset:22528
	ds_read_b128 v[212:215], v242 offset:23552
	s_mov_b64 exec, s[98:99]
	global_load_lds_dwordx4 v[194:195], off
	s_add_i32 m0, s4, 0x2000
	s_add_u32 vcc_lo, s38, 0x40000
	v_lshl_add_u64 v[198:199], s[38:39], 0, v[190:191]
	s_addc_u32 vcc_hi, s39, 0
	s_add_i32 s4, s87, s51
	global_load_lds_dwordx4 v[198:199], off
	v_lshl_add_u64 v[216:217], vcc, 0, v[0:1]
	s_mov_b32 m0, s4
	s_nop 0
	global_load_lds_dwordx4 v[216:217], off
	v_lshl_add_u64 v[216:217], vcc, 0, v[190:191]
	s_add_i32 m0, s4, 0x2000
	s_nop 0
	global_load_lds_dwordx4 v[216:217], off
	v_lshl_add_u64 v[216:217], s[40:41], 0, v[202:203]
	s_mov_b32 m0, s56
	s_nop 0
	global_load_lds_dwordx4 v[216:217], off
	v_lshl_add_u64 v[216:217], s[40:41], 0, v[192:193]
	s_mov_b32 m0, s57
	s_nop 0
	global_load_lds_dwordx4 v[216:217], off
	s_mov_b64 exec, -1
	s_waitcnt vmcnt(8)
	s_waitcnt lgkmcnt(0)
	s_setprio 1
	s_barrier
	v_mfma_f32_16x16x32_bf16 v[62:65], v[126:129], v[166:169], v[62:65]
	v_mfma_f32_16x16x32_bf16 v[58:61], v[134:137], v[166:169], v[58:61]
	v_mfma_f32_16x16x32_bf16 v[46:49], v[126:129], v[174:177], v[46:49]
	v_mfma_f32_16x16x32_bf16 v[42:45], v[134:137], v[174:177], v[42:45]
	v_mfma_f32_16x16x32_bf16 v[30:33], v[126:129], v[182:185], v[30:33]
	v_mfma_f32_16x16x32_bf16 v[26:29], v[134:137], v[182:185], v[26:29]
	v_mfma_f32_16x16x32_bf16 v[14:17], v[126:129], v[208:211], v[14:17]
	v_mfma_f32_16x16x32_bf16 v[10:13], v[134:137], v[208:211], v[10:13]
	v_mfma_f32_16x16x32_bf16 v[62:65], v[130:133], v[170:173], v[62:65]
	v_mfma_f32_16x16x32_bf16 v[58:61], v[138:141], v[170:173], v[58:61]
	v_mfma_f32_16x16x32_bf16 v[46:49], v[130:133], v[178:181], v[46:49]
	v_mfma_f32_16x16x32_bf16 v[42:45], v[138:141], v[178:181], v[42:45]
	v_mfma_f32_16x16x32_bf16 v[30:33], v[130:133], v[186:189], v[30:33]
	v_mfma_f32_16x16x32_bf16 v[26:29], v[138:141], v[186:189], v[26:29]
	v_mfma_f32_16x16x32_bf16 v[14:17], v[130:133], v[212:215], v[14:17]
	v_mfma_f32_16x16x32_bf16 v[10:13], v[138:141], v[212:215], v[10:13]
	v_mfma_f32_16x16x32_bf16 v[54:57], v[142:145], v[166:169], v[54:57]
	v_mfma_f32_16x16x32_bf16 v[50:53], v[158:161], v[166:169], v[50:53]
	v_mfma_f32_16x16x32_bf16 v[38:41], v[142:145], v[174:177], v[38:41]
	v_mfma_f32_16x16x32_bf16 v[34:37], v[158:161], v[174:177], v[34:37]
	v_mfma_f32_16x16x32_bf16 v[22:25], v[142:145], v[182:185], v[22:25]
	v_mfma_f32_16x16x32_bf16 v[18:21], v[158:161], v[182:185], v[18:21]
	v_mfma_f32_16x16x32_bf16 v[6:9], v[142:145], v[208:211], v[6:9]
	v_mfma_f32_16x16x32_bf16 v[2:5], v[158:161], v[208:211], v[2:5]
	v_mfma_f32_16x16x32_bf16 v[54:57], v[146:149], v[170:173], v[54:57]
	v_mfma_f32_16x16x32_bf16 v[50:53], v[162:165], v[170:173], v[50:53]
	v_mfma_f32_16x16x32_bf16 v[38:41], v[146:149], v[178:181], v[38:41]
	v_mfma_f32_16x16x32_bf16 v[34:37], v[162:165], v[178:181], v[34:37]
	v_mfma_f32_16x16x32_bf16 v[22:25], v[146:149], v[186:189], v[22:25]
	v_mfma_f32_16x16x32_bf16 v[18:21], v[162:165], v[186:189], v[18:21]
	v_mfma_f32_16x16x32_bf16 v[6:9], v[146:149], v[212:215], v[6:9]
	v_mfma_f32_16x16x32_bf16 v[2:5], v[162:165], v[212:215], v[2:5]
	s_barrier
	s_setprio 0
	s_add_i32 s4, 0, 0x18000
	s_add_i32 s5, 0, 0x1c000
	v_add_u32_e32 v138, s4, v231
	v_add_u32_e32 v162, s5, v231
	ds_read_b128 v[126:129], v138
	ds_read_b128 v[130:133], v138 offset:1024
	ds_read_b128 v[134:137], v138 offset:2048
	ds_read_b128 v[138:141], v138 offset:3072
	ds_read_b128 v[142:145], v162
	ds_read_b128 v[146:149], v162 offset:1024
	ds_read_b128 v[158:161], v162 offset:2048
	ds_read_b128 v[162:165], v162 offset:3072
	s_add_u32 s40, s40, 0x40000
	s_addc_u32 s41, s41, 0
	s_mov_b32 m0, s58
	v_lshl_add_u64 v[216:217], s[40:41], 0, v[202:203]
	ds_read_b128 v[166:169], v242 offset:32768
	ds_read_b128 v[170:173], v242 offset:33792
	ds_read_b128 v[174:177], v242 offset:34816
	ds_read_b128 v[178:181], v242 offset:35840
	ds_read_b128 v[182:185], v242 offset:36864
	ds_read_b128 v[186:189], v242 offset:37888
	ds_read_b128 v[208:211], v242 offset:38912
	ds_read_b128 v[212:215], v242 offset:39936
	s_mov_b64 exec, s[98:99]
	global_load_lds_dwordx4 v[216:217], off
	v_lshl_add_u64 v[216:217], s[40:41], 0, v[192:193]
	s_mov_b32 m0, s59
	s_nop 0
	global_load_lds_dwordx4 v[216:217], off
	s_mov_b64 exec, -1
	s_waitcnt vmcnt(8)
	s_waitcnt lgkmcnt(0)
	s_setprio 1
	s_barrier
	v_mfma_f32_16x16x32_bf16 v[154:157], v[126:129], v[166:169], v[154:157]
	v_mfma_f32_16x16x32_bf16 v[150:153], v[134:137], v[166:169], v[150:153]
	v_mfma_f32_16x16x32_bf16 v[110:113], v[126:129], v[174:177], v[110:113]
	v_mfma_f32_16x16x32_bf16 v[106:109], v[134:137], v[174:177], v[106:109]
	v_mfma_f32_16x16x32_bf16 v[94:97], v[126:129], v[182:185], v[94:97]
	v_mfma_f32_16x16x32_bf16 v[90:93], v[134:137], v[182:185], v[90:93]
	v_mfma_f32_16x16x32_bf16 v[78:81], v[126:129], v[208:211], v[78:81]
	v_mfma_f32_16x16x32_bf16 v[74:77], v[134:137], v[208:211], v[74:77]
	v_mfma_f32_16x16x32_bf16 v[154:157], v[130:133], v[170:173], v[154:157]
	v_mfma_f32_16x16x32_bf16 v[150:153], v[138:141], v[170:173], v[150:153]
	v_mfma_f32_16x16x32_bf16 v[110:113], v[130:133], v[178:181], v[110:113]
	v_mfma_f32_16x16x32_bf16 v[106:109], v[138:141], v[178:181], v[106:109]
	v_mfma_f32_16x16x32_bf16 v[94:97], v[130:133], v[186:189], v[94:97]
	v_mfma_f32_16x16x32_bf16 v[90:93], v[138:141], v[186:189], v[90:93]
	v_mfma_f32_16x16x32_bf16 v[78:81], v[130:133], v[212:215], v[78:81]
	v_mfma_f32_16x16x32_bf16 v[74:77], v[138:141], v[212:215], v[74:77]
	v_mfma_f32_16x16x32_bf16 v[122:125], v[142:145], v[166:169], v[122:125]
	v_mfma_f32_16x16x32_bf16 v[114:117], v[158:161], v[166:169], v[114:117]
	v_mfma_f32_16x16x32_bf16 v[102:105], v[142:145], v[174:177], v[102:105]
	v_mfma_f32_16x16x32_bf16 v[98:101], v[158:161], v[174:177], v[98:101]
	v_mfma_f32_16x16x32_bf16 v[86:89], v[142:145], v[182:185], v[86:89]
	v_mfma_f32_16x16x32_bf16 v[82:85], v[158:161], v[182:185], v[82:85]
	v_mfma_f32_16x16x32_bf16 v[70:73], v[142:145], v[208:211], v[70:73]
	v_mfma_f32_16x16x32_bf16 v[66:69], v[158:161], v[208:211], v[66:69]
	v_mfma_f32_16x16x32_bf16 v[122:125], v[146:149], v[170:173], v[122:125]
	v_mfma_f32_16x16x32_bf16 v[114:117], v[162:165], v[170:173], v[114:117]
	v_mfma_f32_16x16x32_bf16 v[102:105], v[146:149], v[178:181], v[102:105]
	v_mfma_f32_16x16x32_bf16 v[98:101], v[162:165], v[178:181], v[98:101]
	v_mfma_f32_16x16x32_bf16 v[86:89], v[146:149], v[186:189], v[86:89]
	v_mfma_f32_16x16x32_bf16 v[82:85], v[162:165], v[186:189], v[82:85]
	v_mfma_f32_16x16x32_bf16 v[70:73], v[146:149], v[212:215], v[70:73]
	v_mfma_f32_16x16x32_bf16 v[66:69], v[162:165], v[212:215], v[66:69]
	s_barrier
	s_setprio 0
	s_add_i32 s4, s4, s51
	v_lshl_add_u64 v[194:195], v[194:195], 0, s[90:91]
	s_mov_b32 m0, s4
	ds_read_b128 v[166:169], v242 offset:49152
	ds_read_b128 v[170:173], v242 offset:50176
	ds_read_b128 v[174:177], v242 offset:51200
	ds_read_b128 v[178:181], v242 offset:52224
	ds_read_b128 v[182:185], v242 offset:53248
	ds_read_b128 v[186:189], v242 offset:54272
	ds_read_b128 v[208:211], v242 offset:55296
	ds_read_b128 v[212:215], v242 offset:56320
	s_mov_b64 exec, s[98:99]
	global_load_lds_dwordx4 v[194:195], off
	s_add_i32 m0, s4, 0x2000
	s_add_u32 s38, s38, 0x40080
	v_lshl_add_u64 v[194:195], v[198:199], 0, s[90:91]
	s_addc_u32 s39, s39, 0
	s_add_i32 s4, s5, s51
	global_load_lds_dwordx4 v[194:195], off
	v_lshl_add_u64 v[194:195], s[38:39], 0, v[0:1]
	s_mov_b32 m0, s4
	s_nop 0
	global_load_lds_dwordx4 v[194:195], off
	v_lshl_add_u64 v[194:195], s[38:39], 0, v[190:191]
	s_add_i32 m0, s4, 0x2000
	s_nop 0
	global_load_lds_dwordx4 v[194:195], off
	v_lshl_add_u64 v[194:195], s[36:37], 0, v[202:203]
	s_mov_b32 m0, s68
	s_nop 0
	global_load_lds_dwordx4 v[194:195], off
	v_lshl_add_u64 v[194:195], s[36:37], 0, v[192:193]
	s_mov_b32 m0, s69
	s_nop 0
	global_load_lds_dwordx4 v[194:195], off
	s_mov_b64 exec, -1
	s_waitcnt vmcnt(8)
	s_waitcnt lgkmcnt(0)
	s_setprio 1
	s_barrier
	v_mfma_f32_16x16x32_bf16 v[62:65], v[126:129], v[166:169], v[62:65]
	v_mfma_f32_16x16x32_bf16 v[58:61], v[134:137], v[166:169], v[58:61]
	v_mfma_f32_16x16x32_bf16 v[46:49], v[126:129], v[174:177], v[46:49]
	v_mfma_f32_16x16x32_bf16 v[42:45], v[134:137], v[174:177], v[42:45]
	v_mfma_f32_16x16x32_bf16 v[30:33], v[126:129], v[182:185], v[30:33]
	v_mfma_f32_16x16x32_bf16 v[26:29], v[134:137], v[182:185], v[26:29]
	v_mfma_f32_16x16x32_bf16 v[14:17], v[126:129], v[208:211], v[14:17]
	v_mfma_f32_16x16x32_bf16 v[10:13], v[134:137], v[208:211], v[10:13]
	v_mfma_f32_16x16x32_bf16 v[62:65], v[130:133], v[170:173], v[62:65]
	v_mfma_f32_16x16x32_bf16 v[58:61], v[138:141], v[170:173], v[58:61]
	v_mfma_f32_16x16x32_bf16 v[46:49], v[130:133], v[178:181], v[46:49]
	v_mfma_f32_16x16x32_bf16 v[42:45], v[138:141], v[178:181], v[42:45]
	v_mfma_f32_16x16x32_bf16 v[30:33], v[130:133], v[186:189], v[30:33]
	v_mfma_f32_16x16x32_bf16 v[26:29], v[138:141], v[186:189], v[26:29]
	v_mfma_f32_16x16x32_bf16 v[14:17], v[130:133], v[212:215], v[14:17]
	v_mfma_f32_16x16x32_bf16 v[10:13], v[138:141], v[212:215], v[10:13]
	v_mfma_f32_16x16x32_bf16 v[54:57], v[142:145], v[166:169], v[54:57]
	v_mfma_f32_16x16x32_bf16 v[50:53], v[158:161], v[166:169], v[50:53]
	v_mfma_f32_16x16x32_bf16 v[38:41], v[142:145], v[174:177], v[38:41]
	v_mfma_f32_16x16x32_bf16 v[34:37], v[158:161], v[174:177], v[34:37]
	v_mfma_f32_16x16x32_bf16 v[22:25], v[142:145], v[182:185], v[22:25]
	v_mfma_f32_16x16x32_bf16 v[18:21], v[158:161], v[182:185], v[18:21]
	v_mfma_f32_16x16x32_bf16 v[6:9], v[142:145], v[208:211], v[6:9]
	v_mfma_f32_16x16x32_bf16 v[2:5], v[158:161], v[208:211], v[2:5]
	v_mfma_f32_16x16x32_bf16 v[54:57], v[146:149], v[170:173], v[54:57]
	v_mfma_f32_16x16x32_bf16 v[50:53], v[162:165], v[170:173], v[50:53]
	v_mfma_f32_16x16x32_bf16 v[38:41], v[146:149], v[178:181], v[38:41]
	v_mfma_f32_16x16x32_bf16 v[34:37], v[162:165], v[178:181], v[34:37]
	v_mfma_f32_16x16x32_bf16 v[22:25], v[146:149], v[186:189], v[22:25]
	v_mfma_f32_16x16x32_bf16 v[18:21], v[162:165], v[186:189], v[18:21]
	v_mfma_f32_16x16x32_bf16 v[6:9], v[146:149], v[212:215], v[6:9]
	v_mfma_f32_16x16x32_bf16 v[2:5], v[162:165], v[212:215], v[2:5]
	s_barrier
	s_setprio 0
	s_add_i32 s86, s86, 2
	s_add_u32 s34, s34, 0x100
	s_addc_u32 s35, s35, 0
	s_cmp_gt_u32 s86, 13
	s_cbranch_scc0 .LBB0_773

.LBB0_861:
	s_add_u32 s4, s30, s34
	s_addc_u32 s5, s31, s35
	s_add_u32 s40, s4, 0x100
	s_addc_u32 s41, s5, 0
	s_add_u32 s38, s78, s34
	s_addc_u32 s39, s85, s35
	s_add_u32 s4, s4, 0x180
	s_addc_u32 s5, s5, 0
	s_add_i32 s65, 0, 0x10000
	s_add_i32 s87, 0, 0x14000
	v_add_u32_e32 v162, s65, v152
	v_add_u32_e32 v178, s87, v152
	ds_read_b128 v[146:149], v162
	ds_read_b128 v[154:157], v162 offset:1024
	ds_read_b128 v[158:161], v162 offset:2048
	ds_read_b128 v[162:165], v162 offset:3072
	ds_read_b128 v[166:169], v178
	ds_read_b128 v[170:173], v178 offset:1024
	ds_read_b128 v[174:177], v178 offset:2048
	ds_read_b128 v[178:181], v178 offset:3072
	s_cmpk_eq_i32 s34, 0x700
	s_cselect_b64 s[98:99], s[8:9], -1
	s_cselect_b32 s37, s76, s5
	s_cselect_b32 s36, s75, s4
	s_cselect_b32 s39, s23, s39
	s_cselect_b32 s38, s74, s38
	s_cselect_b32 s41, s25, s41
	s_cselect_b32 s40, s73, s40
	v_lshl_add_u64 v[194:195], v[142:143], 0, s[34:35]
	s_add_i32 m0, s56, 0xc000
	ds_read_b128 v[182:185], v153
	ds_read_b128 v[186:189], v153 offset:1024
	ds_read_b128 v[190:193], v153 offset:2048
	ds_read_b128 v[202:205], v153 offset:3072
	ds_read_b128 v[206:209], v153 offset:4096
	ds_read_b128 v[210:213], v153 offset:5120
	ds_read_b128 v[214:217], v153 offset:6144
	ds_read_b128 v[218:221], v153 offset:7168
	global_load_lds_dwordx4 v[194:195], off
	v_lshl_add_u64 v[194:195], v[144:145], 0, s[34:35]
	s_add_i32 m0, s56, 0xe000
	s_nop 0
	global_load_lds_dwordx4 v[194:195], off
	s_waitcnt vmcnt(8)
	s_waitcnt lgkmcnt(0)
	s_setprio 1
	s_barrier
	v_mfma_f32_16x16x32_bf16 v[126:129], v[146:149], v[182:185], v[126:129]
	v_mfma_f32_16x16x32_bf16 v[122:125], v[158:161], v[182:185], v[122:125]
	v_mfma_f32_16x16x32_bf16 v[110:113], v[146:149], v[190:193], v[110:113]
	v_mfma_f32_16x16x32_bf16 v[106:109], v[158:161], v[190:193], v[106:109]
	v_mfma_f32_16x16x32_bf16 v[94:97], v[146:149], v[206:209], v[94:97]
	v_mfma_f32_16x16x32_bf16 v[90:93], v[158:161], v[206:209], v[90:93]
	v_mfma_f32_16x16x32_bf16 v[78:81], v[146:149], v[214:217], v[78:81]
	v_mfma_f32_16x16x32_bf16 v[74:77], v[158:161], v[214:217], v[74:77]
	v_mfma_f32_16x16x32_bf16 v[126:129], v[154:157], v[186:189], v[126:129]
	v_mfma_f32_16x16x32_bf16 v[122:125], v[162:165], v[186:189], v[122:125]
	v_mfma_f32_16x16x32_bf16 v[110:113], v[154:157], v[202:205], v[110:113]
	v_mfma_f32_16x16x32_bf16 v[106:109], v[162:165], v[202:205], v[106:109]
	v_mfma_f32_16x16x32_bf16 v[94:97], v[154:157], v[210:213], v[94:97]
	v_mfma_f32_16x16x32_bf16 v[90:93], v[162:165], v[210:213], v[90:93]
	v_mfma_f32_16x16x32_bf16 v[78:81], v[154:157], v[218:221], v[78:81]
	v_mfma_f32_16x16x32_bf16 v[74:77], v[162:165], v[218:221], v[74:77]
	v_mfma_f32_16x16x32_bf16 v[118:121], v[166:169], v[182:185], v[118:121]
	v_mfma_f32_16x16x32_bf16 v[114:117], v[174:177], v[182:185], v[114:117]
	v_mfma_f32_16x16x32_bf16 v[102:105], v[166:169], v[190:193], v[102:105]
	v_mfma_f32_16x16x32_bf16 v[98:101], v[174:177], v[190:193], v[98:101]
	v_mfma_f32_16x16x32_bf16 v[86:89], v[166:169], v[206:209], v[86:89]
	v_mfma_f32_16x16x32_bf16 v[82:85], v[174:177], v[206:209], v[82:85]
	v_mfma_f32_16x16x32_bf16 v[70:73], v[166:169], v[214:217], v[70:73]
	v_mfma_f32_16x16x32_bf16 v[66:69], v[174:177], v[214:217], v[66:69]
	v_mfma_f32_16x16x32_bf16 v[118:121], v[170:173], v[186:189], v[118:121]
	v_mfma_f32_16x16x32_bf16 v[114:117], v[178:181], v[186:189], v[114:117]
	v_mfma_f32_16x16x32_bf16 v[102:105], v[170:173], v[202:205], v[102:105]
	v_mfma_f32_16x16x32_bf16 v[98:101], v[178:181], v[202:205], v[98:101]
	v_mfma_f32_16x16x32_bf16 v[86:89], v[170:173], v[210:213], v[86:89]
	v_mfma_f32_16x16x32_bf16 v[82:85], v[178:181], v[210:213], v[82:85]
	v_mfma_f32_16x16x32_bf16 v[70:73], v[170:173], v[218:221], v[70:73]
	v_mfma_f32_16x16x32_bf16 v[66:69], v[178:181], v[218:221], v[66:69]
	s_barrier
	s_setprio 0
	s_add_i32 s4, s65, s51
	v_lshl_add_u64 v[194:195], s[38:39], 0, v[134:135]
	s_mov_b32 m0, s4
	ds_read_b128 v[182:185], v153 offset:16384
	ds_read_b128 v[186:189], v153 offset:17408
	ds_read_b128 v[190:193], v153 offset:18432
	ds_read_b128 v[202:205], v153 offset:19456
	ds_read_b128 v[206:209], v153 offset:20480
	ds_read_b128 v[210:213], v153 offset:21504
	ds_read_b128 v[214:217], v153 offset:22528
	ds_read_b128 v[218:221], v153 offset:23552
	s_mov_b64 exec, s[98:99]
	global_load_lds_dwordx4 v[194:195], off
	s_add_i32 m0, s4, 0x2000
	s_add_u32 vcc_lo, s38, 0x40000
	v_lshl_add_u64 v[198:199], s[38:39], 0, v[130:131]
	s_addc_u32 vcc_hi, s39, 0
	s_add_i32 s4, s87, s51
	global_load_lds_dwordx4 v[198:199], off
	v_lshl_add_u64 v[222:223], vcc, 0, v[134:135]
	s_mov_b32 m0, s4
	s_nop 0
	global_load_lds_dwordx4 v[222:223], off
	v_lshl_add_u64 v[222:223], vcc, 0, v[130:131]
	s_add_i32 m0, s4, 0x2000
	s_nop 0
	global_load_lds_dwordx4 v[222:223], off
	v_lshl_add_u64 v[222:223], s[40:41], 0, v[136:137]
	s_mov_b32 m0, s56
	s_nop 0
	global_load_lds_dwordx4 v[222:223], off
	v_lshl_add_u64 v[222:223], s[40:41], 0, v[132:133]
	s_mov_b32 m0, s57
	s_nop 0
	global_load_lds_dwordx4 v[222:223], off
	s_mov_b64 exec, -1
	s_waitcnt vmcnt(8)
	s_waitcnt lgkmcnt(0)
	s_setprio 1
	s_barrier
	v_mfma_f32_16x16x32_bf16 v[62:65], v[146:149], v[182:185], v[62:65]
	v_mfma_f32_16x16x32_bf16 v[58:61], v[158:161], v[182:185], v[58:61]
	v_mfma_f32_16x16x32_bf16 v[46:49], v[146:149], v[190:193], v[46:49]
	v_mfma_f32_16x16x32_bf16 v[42:45], v[158:161], v[190:193], v[42:45]
	v_mfma_f32_16x16x32_bf16 v[30:33], v[146:149], v[206:209], v[30:33]
	v_mfma_f32_16x16x32_bf16 v[26:29], v[158:161], v[206:209], v[26:29]
	v_mfma_f32_16x16x32_bf16 v[14:17], v[146:149], v[214:217], v[14:17]
	v_mfma_f32_16x16x32_bf16 v[10:13], v[158:161], v[214:217], v[10:13]
	v_mfma_f32_16x16x32_bf16 v[62:65], v[154:157], v[186:189], v[62:65]
	v_mfma_f32_16x16x32_bf16 v[58:61], v[162:165], v[186:189], v[58:61]
	v_mfma_f32_16x16x32_bf16 v[46:49], v[154:157], v[202:205], v[46:49]
	v_mfma_f32_16x16x32_bf16 v[42:45], v[162:165], v[202:205], v[42:45]
	v_mfma_f32_16x16x32_bf16 v[30:33], v[154:157], v[210:213], v[30:33]
	v_mfma_f32_16x16x32_bf16 v[26:29], v[162:165], v[210:213], v[26:29]
	v_mfma_f32_16x16x32_bf16 v[14:17], v[154:157], v[218:221], v[14:17]
	v_mfma_f32_16x16x32_bf16 v[10:13], v[162:165], v[218:221], v[10:13]
	v_mfma_f32_16x16x32_bf16 v[54:57], v[166:169], v[182:185], v[54:57]
	v_mfma_f32_16x16x32_bf16 v[50:53], v[174:177], v[182:185], v[50:53]
	v_mfma_f32_16x16x32_bf16 v[38:41], v[166:169], v[190:193], v[38:41]
	v_mfma_f32_16x16x32_bf16 v[34:37], v[174:177], v[190:193], v[34:37]
	v_mfma_f32_16x16x32_bf16 v[22:25], v[166:169], v[206:209], v[22:25]
	v_mfma_f32_16x16x32_bf16 v[18:21], v[174:177], v[206:209], v[18:21]
	v_mfma_f32_16x16x32_bf16 v[6:9], v[166:169], v[214:217], v[6:9]
	v_mfma_f32_16x16x32_bf16 v[2:5], v[174:177], v[214:217], v[2:5]
	v_mfma_f32_16x16x32_bf16 v[54:57], v[170:173], v[186:189], v[54:57]
	v_mfma_f32_16x16x32_bf16 v[50:53], v[178:181], v[186:189], v[50:53]
	v_mfma_f32_16x16x32_bf16 v[38:41], v[170:173], v[202:205], v[38:41]
	v_mfma_f32_16x16x32_bf16 v[34:37], v[178:181], v[202:205], v[34:37]
	v_mfma_f32_16x16x32_bf16 v[22:25], v[170:173], v[210:213], v[22:25]
	v_mfma_f32_16x16x32_bf16 v[18:21], v[178:181], v[210:213], v[18:21]
	v_mfma_f32_16x16x32_bf16 v[6:9], v[170:173], v[218:221], v[6:9]
	v_mfma_f32_16x16x32_bf16 v[2:5], v[178:181], v[218:221], v[2:5]
	s_barrier
	s_setprio 0
	s_add_i32 s4, 0, 0x18000
	s_add_i32 s5, 0, 0x1c000
	v_add_u32_e32 v162, s4, v152
	v_add_u32_e32 v178, s5, v152
	ds_read_b128 v[146:149], v162
	ds_read_b128 v[154:157], v162 offset:1024
	ds_read_b128 v[158:161], v162 offset:2048
	ds_read_b128 v[162:165], v162 offset:3072
	ds_read_b128 v[166:169], v178
	ds_read_b128 v[170:173], v178 offset:1024
	ds_read_b128 v[174:177], v178 offset:2048
	ds_read_b128 v[178:181], v178 offset:3072
	s_add_u32 s40, s40, 0x40000
	s_addc_u32 s41, s41, 0
	s_mov_b32 m0, s58
	v_lshl_add_u64 v[222:223], s[40:41], 0, v[136:137]
	ds_read_b128 v[182:185], v153 offset:32768
	ds_read_b128 v[186:189], v153 offset:33792
	ds_read_b128 v[190:193], v153 offset:34816
	ds_read_b128 v[202:205], v153 offset:35840
	ds_read_b128 v[206:209], v153 offset:36864
	ds_read_b128 v[210:213], v153 offset:37888
	ds_read_b128 v[214:217], v153 offset:38912
	ds_read_b128 v[218:221], v153 offset:39936
	s_mov_b64 exec, s[98:99]
	global_load_lds_dwordx4 v[222:223], off
	v_lshl_add_u64 v[222:223], s[40:41], 0, v[132:133]
	s_mov_b32 m0, s59
	s_nop 0
	global_load_lds_dwordx4 v[222:223], off
	s_mov_b64 exec, -1
	s_waitcnt vmcnt(8)
	s_waitcnt lgkmcnt(0)
	s_setprio 1
	s_barrier
	v_mfma_f32_16x16x32_bf16 v[126:129], v[146:149], v[182:185], v[126:129]
	v_mfma_f32_16x16x32_bf16 v[122:125], v[158:161], v[182:185], v[122:125]
	v_mfma_f32_16x16x32_bf16 v[110:113], v[146:149], v[190:193], v[110:113]
	v_mfma_f32_16x16x32_bf16 v[106:109], v[158:161], v[190:193], v[106:109]
	v_mfma_f32_16x16x32_bf16 v[94:97], v[146:149], v[206:209], v[94:97]
	v_mfma_f32_16x16x32_bf16 v[90:93], v[158:161], v[206:209], v[90:93]
	v_mfma_f32_16x16x32_bf16 v[78:81], v[146:149], v[214:217], v[78:81]
	v_mfma_f32_16x16x32_bf16 v[74:77], v[158:161], v[214:217], v[74:77]
	v_mfma_f32_16x16x32_bf16 v[126:129], v[154:157], v[186:189], v[126:129]
	v_mfma_f32_16x16x32_bf16 v[122:125], v[162:165], v[186:189], v[122:125]
	v_mfma_f32_16x16x32_bf16 v[110:113], v[154:157], v[202:205], v[110:113]
	v_mfma_f32_16x16x32_bf16 v[106:109], v[162:165], v[202:205], v[106:109]
	v_mfma_f32_16x16x32_bf16 v[94:97], v[154:157], v[210:213], v[94:97]
	v_mfma_f32_16x16x32_bf16 v[90:93], v[162:165], v[210:213], v[90:93]
	v_mfma_f32_16x16x32_bf16 v[78:81], v[154:157], v[218:221], v[78:81]
	v_mfma_f32_16x16x32_bf16 v[74:77], v[162:165], v[218:221], v[74:77]
	v_mfma_f32_16x16x32_bf16 v[118:121], v[166:169], v[182:185], v[118:121]
	v_mfma_f32_16x16x32_bf16 v[114:117], v[174:177], v[182:185], v[114:117]
	v_mfma_f32_16x16x32_bf16 v[102:105], v[166:169], v[190:193], v[102:105]
	v_mfma_f32_16x16x32_bf16 v[98:101], v[174:177], v[190:193], v[98:101]
	v_mfma_f32_16x16x32_bf16 v[86:89], v[166:169], v[206:209], v[86:89]
	v_mfma_f32_16x16x32_bf16 v[82:85], v[174:177], v[206:209], v[82:85]
	v_mfma_f32_16x16x32_bf16 v[70:73], v[166:169], v[214:217], v[70:73]
	v_mfma_f32_16x16x32_bf16 v[66:69], v[174:177], v[214:217], v[66:69]
	v_mfma_f32_16x16x32_bf16 v[118:121], v[170:173], v[186:189], v[118:121]
	v_mfma_f32_16x16x32_bf16 v[114:117], v[178:181], v[186:189], v[114:117]
	v_mfma_f32_16x16x32_bf16 v[102:105], v[170:173], v[202:205], v[102:105]
	v_mfma_f32_16x16x32_bf16 v[98:101], v[178:181], v[202:205], v[98:101]
	v_mfma_f32_16x16x32_bf16 v[86:89], v[170:173], v[210:213], v[86:89]
	v_mfma_f32_16x16x32_bf16 v[82:85], v[178:181], v[210:213], v[82:85]
	v_mfma_f32_16x16x32_bf16 v[70:73], v[170:173], v[218:221], v[70:73]
	v_mfma_f32_16x16x32_bf16 v[66:69], v[178:181], v[218:221], v[66:69]
	s_barrier
	s_setprio 0
	s_add_i32 s4, s4, s51
	v_lshl_add_u64 v[194:195], v[194:195], 0, s[90:91]
	s_mov_b32 m0, s4
	ds_read_b128 v[182:185], v153 offset:49152
	ds_read_b128 v[186:189], v153 offset:50176
	ds_read_b128 v[190:193], v153 offset:51200
	ds_read_b128 v[202:205], v153 offset:52224
	ds_read_b128 v[206:209], v153 offset:53248
	ds_read_b128 v[210:213], v153 offset:54272
	ds_read_b128 v[214:217], v153 offset:55296
	ds_read_b128 v[218:221], v153 offset:56320
	s_mov_b64 exec, s[98:99]
	global_load_lds_dwordx4 v[194:195], off
	s_add_i32 m0, s4, 0x2000
	s_add_u32 s38, s38, 0x40080
	v_lshl_add_u64 v[194:195], v[198:199], 0, s[90:91]
	s_addc_u32 s39, s39, 0
	s_add_i32 s4, s5, s51
	global_load_lds_dwordx4 v[194:195], off
	v_lshl_add_u64 v[194:195], s[38:39], 0, v[134:135]
	s_mov_b32 m0, s4
	s_nop 0
	global_load_lds_dwordx4 v[194:195], off
	v_lshl_add_u64 v[194:195], s[38:39], 0, v[130:131]
	s_add_i32 m0, s4, 0x2000
	s_nop 0
	global_load_lds_dwordx4 v[194:195], off
	v_lshl_add_u64 v[194:195], s[36:37], 0, v[136:137]
	s_mov_b32 m0, s68
	s_nop 0
	global_load_lds_dwordx4 v[194:195], off
	v_lshl_add_u64 v[194:195], s[36:37], 0, v[132:133]
	s_mov_b32 m0, s69
	s_nop 0
	global_load_lds_dwordx4 v[194:195], off
	s_mov_b64 exec, -1
	s_waitcnt vmcnt(8)
	s_waitcnt lgkmcnt(0)
	s_setprio 1
	s_barrier
	v_mfma_f32_16x16x32_bf16 v[62:65], v[146:149], v[182:185], v[62:65]
	v_mfma_f32_16x16x32_bf16 v[58:61], v[158:161], v[182:185], v[58:61]
	v_mfma_f32_16x16x32_bf16 v[46:49], v[146:149], v[190:193], v[46:49]
	v_mfma_f32_16x16x32_bf16 v[42:45], v[158:161], v[190:193], v[42:45]
	v_mfma_f32_16x16x32_bf16 v[30:33], v[146:149], v[206:209], v[30:33]
	v_mfma_f32_16x16x32_bf16 v[26:29], v[158:161], v[206:209], v[26:29]
	v_mfma_f32_16x16x32_bf16 v[14:17], v[146:149], v[214:217], v[14:17]
	v_mfma_f32_16x16x32_bf16 v[10:13], v[158:161], v[214:217], v[10:13]
	v_mfma_f32_16x16x32_bf16 v[62:65], v[154:157], v[186:189], v[62:65]
	v_mfma_f32_16x16x32_bf16 v[58:61], v[162:165], v[186:189], v[58:61]
	v_mfma_f32_16x16x32_bf16 v[46:49], v[154:157], v[202:205], v[46:49]
	v_mfma_f32_16x16x32_bf16 v[42:45], v[162:165], v[202:205], v[42:45]
	v_mfma_f32_16x16x32_bf16 v[30:33], v[154:157], v[210:213], v[30:33]
	v_mfma_f32_16x16x32_bf16 v[26:29], v[162:165], v[210:213], v[26:29]
	v_mfma_f32_16x16x32_bf16 v[14:17], v[154:157], v[218:221], v[14:17]
	v_mfma_f32_16x16x32_bf16 v[10:13], v[162:165], v[218:221], v[10:13]
	v_mfma_f32_16x16x32_bf16 v[54:57], v[166:169], v[182:185], v[54:57]
	v_mfma_f32_16x16x32_bf16 v[50:53], v[174:177], v[182:185], v[50:53]
	v_mfma_f32_16x16x32_bf16 v[38:41], v[166:169], v[190:193], v[38:41]
	v_mfma_f32_16x16x32_bf16 v[34:37], v[174:177], v[190:193], v[34:37]
	v_mfma_f32_16x16x32_bf16 v[22:25], v[166:169], v[206:209], v[22:25]
	v_mfma_f32_16x16x32_bf16 v[18:21], v[174:177], v[206:209], v[18:21]
	v_mfma_f32_16x16x32_bf16 v[6:9], v[166:169], v[214:217], v[6:9]
	v_mfma_f32_16x16x32_bf16 v[2:5], v[174:177], v[214:217], v[2:5]
	v_mfma_f32_16x16x32_bf16 v[54:57], v[170:173], v[186:189], v[54:57]
	v_mfma_f32_16x16x32_bf16 v[50:53], v[178:181], v[186:189], v[50:53]
	v_mfma_f32_16x16x32_bf16 v[38:41], v[170:173], v[202:205], v[38:41]
	v_mfma_f32_16x16x32_bf16 v[34:37], v[178:181], v[202:205], v[34:37]
	v_mfma_f32_16x16x32_bf16 v[22:25], v[170:173], v[210:213], v[22:25]
	v_mfma_f32_16x16x32_bf16 v[18:21], v[178:181], v[210:213], v[18:21]
	v_mfma_f32_16x16x32_bf16 v[6:9], v[170:173], v[218:221], v[6:9]
	v_mfma_f32_16x16x32_bf16 v[2:5], v[178:181], v[218:221], v[2:5]
	s_barrier
	s_setprio 0
	s_add_i32 s86, s86, 2
	s_add_u32 s34, s34, 0x100
	s_addc_u32 s35, s35, 0
	s_cmp_gt_u32 s86, 13
	s_cbranch_scc0 .LBB0_861

.LBB0_915:
	s_add_u32 s4, s34, s36
	s_addc_u32 s5, s35, s37
	s_add_u32 s42, s4, 0x100
	s_addc_u32 s43, s5, 0
	s_add_u32 s40, s76, s36
	s_addc_u32 s41, s78, s37
	s_add_u32 s4, s4, 0x180
	s_addc_u32 s5, s5, 0
	s_add_i32 s85, 0, 0x10000
	s_add_i32 vcc_lo, 0, 0x14000
	v_add_u32_e32 v138, s85, v231
	v_add_u32_e32 v162, vcc_lo, v231
	ds_read_b128 v[126:129], v138
	ds_read_b128 v[130:133], v138 offset:1024
	ds_read_b128 v[134:137], v138 offset:2048
	ds_read_b128 v[138:141], v138 offset:3072
	ds_read_b128 v[142:145], v162
	ds_read_b128 v[146:149], v162 offset:1024
	ds_read_b128 v[158:161], v162 offset:2048
	ds_read_b128 v[162:165], v162 offset:3072
	s_cmpk_eq_i32 s36, 0x1f00
	s_cselect_b64 s[98:99], s[8:9], -1
	s_cselect_b32 s39, s75, s5
	s_cselect_b32 s38, s74, s4
	s_cselect_b32 s41, s25, s41
	s_cselect_b32 s40, s73, s40
	s_cselect_b32 s43, s27, s43
	s_cselect_b32 s42, s72, s42
	v_lshl_add_u64 v[194:195], v[118:119], 0, s[36:37]
	s_add_i32 m0, s58, 0xc000
	ds_read_b128 v[166:169], v242
	ds_read_b128 v[170:173], v242 offset:1024
	ds_read_b128 v[174:177], v242 offset:2048
	ds_read_b128 v[178:181], v242 offset:3072
	ds_read_b128 v[182:185], v242 offset:4096
	ds_read_b128 v[186:189], v242 offset:5120
	ds_read_b128 v[208:211], v242 offset:6144
	ds_read_b128 v[212:215], v242 offset:7168
	global_load_lds_dwordx4 v[194:195], off
	v_lshl_add_u64 v[194:195], v[120:121], 0, s[36:37]
	s_add_i32 m0, s58, 0xe000
	s_nop 0
	global_load_lds_dwordx4 v[194:195], off
	s_waitcnt vmcnt(8)
	s_waitcnt lgkmcnt(0)
	s_setprio 1
	s_barrier
	v_mfma_f32_16x16x32_bf16 v[154:157], v[126:129], v[166:169], v[154:157]
	v_mfma_f32_16x16x32_bf16 v[150:153], v[134:137], v[166:169], v[150:153]
	v_mfma_f32_16x16x32_bf16 v[110:113], v[126:129], v[174:177], v[110:113]
	v_mfma_f32_16x16x32_bf16 v[106:109], v[134:137], v[174:177], v[106:109]
	v_mfma_f32_16x16x32_bf16 v[94:97], v[126:129], v[182:185], v[94:97]
	v_mfma_f32_16x16x32_bf16 v[90:93], v[134:137], v[182:185], v[90:93]
	v_mfma_f32_16x16x32_bf16 v[78:81], v[126:129], v[208:211], v[78:81]
	v_mfma_f32_16x16x32_bf16 v[74:77], v[134:137], v[208:211], v[74:77]
	v_mfma_f32_16x16x32_bf16 v[154:157], v[130:133], v[170:173], v[154:157]
	v_mfma_f32_16x16x32_bf16 v[150:153], v[138:141], v[170:173], v[150:153]
	v_mfma_f32_16x16x32_bf16 v[110:113], v[130:133], v[178:181], v[110:113]
	v_mfma_f32_16x16x32_bf16 v[106:109], v[138:141], v[178:181], v[106:109]
	v_mfma_f32_16x16x32_bf16 v[94:97], v[130:133], v[186:189], v[94:97]
	v_mfma_f32_16x16x32_bf16 v[90:93], v[138:141], v[186:189], v[90:93]
	v_mfma_f32_16x16x32_bf16 v[78:81], v[130:133], v[212:215], v[78:81]
	v_mfma_f32_16x16x32_bf16 v[74:77], v[138:141], v[212:215], v[74:77]
	v_mfma_f32_16x16x32_bf16 v[122:125], v[142:145], v[166:169], v[122:125]
	v_mfma_f32_16x16x32_bf16 v[114:117], v[158:161], v[166:169], v[114:117]
	v_mfma_f32_16x16x32_bf16 v[102:105], v[142:145], v[174:177], v[102:105]
	v_mfma_f32_16x16x32_bf16 v[98:101], v[158:161], v[174:177], v[98:101]
	v_mfma_f32_16x16x32_bf16 v[86:89], v[142:145], v[182:185], v[86:89]
	v_mfma_f32_16x16x32_bf16 v[82:85], v[158:161], v[182:185], v[82:85]
	v_mfma_f32_16x16x32_bf16 v[70:73], v[142:145], v[208:211], v[70:73]
	v_mfma_f32_16x16x32_bf16 v[66:69], v[158:161], v[208:211], v[66:69]
	v_mfma_f32_16x16x32_bf16 v[122:125], v[146:149], v[170:173], v[122:125]
	v_mfma_f32_16x16x32_bf16 v[114:117], v[162:165], v[170:173], v[114:117]
	v_mfma_f32_16x16x32_bf16 v[102:105], v[146:149], v[178:181], v[102:105]
	v_mfma_f32_16x16x32_bf16 v[98:101], v[162:165], v[178:181], v[98:101]
	v_mfma_f32_16x16x32_bf16 v[86:89], v[146:149], v[186:189], v[86:89]
	v_mfma_f32_16x16x32_bf16 v[82:85], v[162:165], v[186:189], v[82:85]
	v_mfma_f32_16x16x32_bf16 v[70:73], v[146:149], v[212:215], v[70:73]
	v_mfma_f32_16x16x32_bf16 v[66:69], v[162:165], v[212:215], v[66:69]
	s_barrier
	s_setprio 0
	s_add_i32 s4, s85, s57
	v_lshl_add_u64 v[194:195], s[40:41], 0, v[0:1]
	s_mov_b32 m0, s4
	ds_read_b128 v[166:169], v242 offset:16384
	ds_read_b128 v[170:173], v242 offset:17408
	ds_read_b128 v[174:177], v242 offset:18432
	ds_read_b128 v[178:181], v242 offset:19456
	ds_read_b128 v[182:185], v242 offset:20480
	ds_read_b128 v[186:189], v242 offset:21504
	ds_read_b128 v[208:211], v242 offset:22528
	ds_read_b128 v[212:215], v242 offset:23552
	s_mov_b64 exec, s[98:99]
	global_load_lds_dwordx4 v[194:195], off
	s_add_i32 m0, s4, 0x2000
	s_add_u32 s86, s40, 0x100000
	v_lshl_add_u64 v[198:199], s[40:41], 0, v[190:191]
	s_addc_u32 s87, s41, 0
	s_add_i32 s4, vcc_lo, s57
	global_load_lds_dwordx4 v[198:199], off
	v_lshl_add_u64 v[216:217], s[86:87], 0, v[0:1]
	s_mov_b32 m0, s4
	s_nop 0
	global_load_lds_dwordx4 v[216:217], off
	v_lshl_add_u64 v[216:217], s[86:87], 0, v[190:191]
	s_add_i32 m0, s4, 0x2000
	s_nop 0
	global_load_lds_dwordx4 v[216:217], off
	v_lshl_add_u64 v[216:217], s[42:43], 0, v[202:203]
	s_mov_b32 m0, s58
	s_nop 0
	global_load_lds_dwordx4 v[216:217], off
	v_lshl_add_u64 v[216:217], s[42:43], 0, v[192:193]
	s_mov_b32 m0, s59
	s_nop 0
	global_load_lds_dwordx4 v[216:217], off
	s_mov_b64 exec, -1
	s_waitcnt vmcnt(8)
	s_waitcnt lgkmcnt(0)
	s_setprio 1
	s_barrier
	v_mfma_f32_16x16x32_bf16 v[62:65], v[126:129], v[166:169], v[62:65]
	v_mfma_f32_16x16x32_bf16 v[58:61], v[134:137], v[166:169], v[58:61]
	v_mfma_f32_16x16x32_bf16 v[46:49], v[126:129], v[174:177], v[46:49]
	v_mfma_f32_16x16x32_bf16 v[42:45], v[134:137], v[174:177], v[42:45]
	v_mfma_f32_16x16x32_bf16 v[30:33], v[126:129], v[182:185], v[30:33]
	v_mfma_f32_16x16x32_bf16 v[26:29], v[134:137], v[182:185], v[26:29]
	v_mfma_f32_16x16x32_bf16 v[14:17], v[126:129], v[208:211], v[14:17]
	v_mfma_f32_16x16x32_bf16 v[10:13], v[134:137], v[208:211], v[10:13]
	v_mfma_f32_16x16x32_bf16 v[62:65], v[130:133], v[170:173], v[62:65]
	v_mfma_f32_16x16x32_bf16 v[58:61], v[138:141], v[170:173], v[58:61]
	v_mfma_f32_16x16x32_bf16 v[46:49], v[130:133], v[178:181], v[46:49]
	v_mfma_f32_16x16x32_bf16 v[42:45], v[138:141], v[178:181], v[42:45]
	v_mfma_f32_16x16x32_bf16 v[30:33], v[130:133], v[186:189], v[30:33]
	v_mfma_f32_16x16x32_bf16 v[26:29], v[138:141], v[186:189], v[26:29]
	v_mfma_f32_16x16x32_bf16 v[14:17], v[130:133], v[212:215], v[14:17]
	v_mfma_f32_16x16x32_bf16 v[10:13], v[138:141], v[212:215], v[10:13]
	v_mfma_f32_16x16x32_bf16 v[54:57], v[142:145], v[166:169], v[54:57]
	v_mfma_f32_16x16x32_bf16 v[50:53], v[158:161], v[166:169], v[50:53]
	v_mfma_f32_16x16x32_bf16 v[38:41], v[142:145], v[174:177], v[38:41]
	v_mfma_f32_16x16x32_bf16 v[34:37], v[158:161], v[174:177], v[34:37]
	v_mfma_f32_16x16x32_bf16 v[22:25], v[142:145], v[182:185], v[22:25]
	v_mfma_f32_16x16x32_bf16 v[18:21], v[158:161], v[182:185], v[18:21]
	v_mfma_f32_16x16x32_bf16 v[6:9], v[142:145], v[208:211], v[6:9]
	v_mfma_f32_16x16x32_bf16 v[2:5], v[158:161], v[208:211], v[2:5]
	v_mfma_f32_16x16x32_bf16 v[54:57], v[146:149], v[170:173], v[54:57]
	v_mfma_f32_16x16x32_bf16 v[50:53], v[162:165], v[170:173], v[50:53]
	v_mfma_f32_16x16x32_bf16 v[38:41], v[146:149], v[178:181], v[38:41]
	v_mfma_f32_16x16x32_bf16 v[34:37], v[162:165], v[178:181], v[34:37]
	v_mfma_f32_16x16x32_bf16 v[22:25], v[146:149], v[186:189], v[22:25]
	v_mfma_f32_16x16x32_bf16 v[18:21], v[162:165], v[186:189], v[18:21]
	v_mfma_f32_16x16x32_bf16 v[6:9], v[146:149], v[212:215], v[6:9]
	v_mfma_f32_16x16x32_bf16 v[2:5], v[162:165], v[212:215], v[2:5]
	s_barrier
	s_setprio 0
	s_add_i32 s4, 0, 0x18000
	s_add_i32 s5, 0, 0x1c000
	v_add_u32_e32 v138, s4, v231
	v_add_u32_e32 v162, s5, v231
	ds_read_b128 v[126:129], v138
	ds_read_b128 v[130:133], v138 offset:1024
	ds_read_b128 v[134:137], v138 offset:2048
	ds_read_b128 v[138:141], v138 offset:3072
	ds_read_b128 v[142:145], v162
	ds_read_b128 v[146:149], v162 offset:1024
	ds_read_b128 v[158:161], v162 offset:2048
	ds_read_b128 v[162:165], v162 offset:3072
	s_add_u32 s42, s42, 0x100000
	s_addc_u32 s43, s43, 0
	s_mov_b32 m0, s65
	v_lshl_add_u64 v[216:217], s[42:43], 0, v[202:203]
	ds_read_b128 v[166:169], v242 offset:32768
	ds_read_b128 v[170:173], v242 offset:33792
	ds_read_b128 v[174:177], v242 offset:34816
	ds_read_b128 v[178:181], v242 offset:35840
	ds_read_b128 v[182:185], v242 offset:36864
	ds_read_b128 v[186:189], v242 offset:37888
	ds_read_b128 v[208:211], v242 offset:38912
	ds_read_b128 v[212:215], v242 offset:39936
	s_mov_b64 exec, s[98:99]
	global_load_lds_dwordx4 v[216:217], off
	v_lshl_add_u64 v[216:217], s[42:43], 0, v[192:193]
	s_mov_b32 m0, s68
	s_nop 0
	global_load_lds_dwordx4 v[216:217], off
	s_mov_b64 exec, -1
	s_waitcnt vmcnt(8)
	s_waitcnt lgkmcnt(0)
	s_setprio 1
	s_barrier
	v_mfma_f32_16x16x32_bf16 v[154:157], v[126:129], v[166:169], v[154:157]
	v_mfma_f32_16x16x32_bf16 v[150:153], v[134:137], v[166:169], v[150:153]
	v_mfma_f32_16x16x32_bf16 v[110:113], v[126:129], v[174:177], v[110:113]
	v_mfma_f32_16x16x32_bf16 v[106:109], v[134:137], v[174:177], v[106:109]
	v_mfma_f32_16x16x32_bf16 v[94:97], v[126:129], v[182:185], v[94:97]
	v_mfma_f32_16x16x32_bf16 v[90:93], v[134:137], v[182:185], v[90:93]
	v_mfma_f32_16x16x32_bf16 v[78:81], v[126:129], v[208:211], v[78:81]
	v_mfma_f32_16x16x32_bf16 v[74:77], v[134:137], v[208:211], v[74:77]
	v_mfma_f32_16x16x32_bf16 v[154:157], v[130:133], v[170:173], v[154:157]
	v_mfma_f32_16x16x32_bf16 v[150:153], v[138:141], v[170:173], v[150:153]
	v_mfma_f32_16x16x32_bf16 v[110:113], v[130:133], v[178:181], v[110:113]
	v_mfma_f32_16x16x32_bf16 v[106:109], v[138:141], v[178:181], v[106:109]
	v_mfma_f32_16x16x32_bf16 v[94:97], v[130:133], v[186:189], v[94:97]
	v_mfma_f32_16x16x32_bf16 v[90:93], v[138:141], v[186:189], v[90:93]
	v_mfma_f32_16x16x32_bf16 v[78:81], v[130:133], v[212:215], v[78:81]
	v_mfma_f32_16x16x32_bf16 v[74:77], v[138:141], v[212:215], v[74:77]
	v_mfma_f32_16x16x32_bf16 v[122:125], v[142:145], v[166:169], v[122:125]
	v_mfma_f32_16x16x32_bf16 v[114:117], v[158:161], v[166:169], v[114:117]
	v_mfma_f32_16x16x32_bf16 v[102:105], v[142:145], v[174:177], v[102:105]
	v_mfma_f32_16x16x32_bf16 v[98:101], v[158:161], v[174:177], v[98:101]
	v_mfma_f32_16x16x32_bf16 v[86:89], v[142:145], v[182:185], v[86:89]
	v_mfma_f32_16x16x32_bf16 v[82:85], v[158:161], v[182:185], v[82:85]
	v_mfma_f32_16x16x32_bf16 v[70:73], v[142:145], v[208:211], v[70:73]
	v_mfma_f32_16x16x32_bf16 v[66:69], v[158:161], v[208:211], v[66:69]
	v_mfma_f32_16x16x32_bf16 v[122:125], v[146:149], v[170:173], v[122:125]
	v_mfma_f32_16x16x32_bf16 v[114:117], v[162:165], v[170:173], v[114:117]
	v_mfma_f32_16x16x32_bf16 v[102:105], v[146:149], v[178:181], v[102:105]
	v_mfma_f32_16x16x32_bf16 v[98:101], v[162:165], v[178:181], v[98:101]
	v_mfma_f32_16x16x32_bf16 v[86:89], v[146:149], v[186:189], v[86:89]
	v_mfma_f32_16x16x32_bf16 v[82:85], v[162:165], v[186:189], v[82:85]
	v_mfma_f32_16x16x32_bf16 v[70:73], v[146:149], v[212:215], v[70:73]
	v_mfma_f32_16x16x32_bf16 v[66:69], v[162:165], v[212:215], v[66:69]
	s_barrier
	s_setprio 0
	s_add_i32 s4, s4, s57
	v_lshl_add_u64 v[194:195], v[194:195], 0, s[90:91]
	s_mov_b32 m0, s4
	ds_read_b128 v[166:169], v242 offset:49152
	ds_read_b128 v[170:173], v242 offset:50176
	ds_read_b128 v[174:177], v242 offset:51200
	ds_read_b128 v[178:181], v242 offset:52224
	ds_read_b128 v[182:185], v242 offset:53248
	ds_read_b128 v[186:189], v242 offset:54272
	ds_read_b128 v[208:211], v242 offset:55296
	ds_read_b128 v[212:215], v242 offset:56320
	s_mov_b64 exec, s[98:99]
	global_load_lds_dwordx4 v[194:195], off
	s_add_i32 m0, s4, 0x2000
	s_add_u32 s40, s40, 0x100080
	v_lshl_add_u64 v[194:195], v[198:199], 0, s[90:91]
	s_addc_u32 s41, s41, 0
	s_add_i32 s4, s5, s57
	global_load_lds_dwordx4 v[194:195], off
	v_lshl_add_u64 v[194:195], s[40:41], 0, v[0:1]
	s_mov_b32 m0, s4
	s_nop 0
	global_load_lds_dwordx4 v[194:195], off
	v_lshl_add_u64 v[194:195], s[40:41], 0, v[190:191]
	s_add_i32 m0, s4, 0x2000
	s_nop 0
	global_load_lds_dwordx4 v[194:195], off
	v_lshl_add_u64 v[194:195], s[38:39], 0, v[202:203]
	s_mov_b32 m0, s54
	s_nop 0
	global_load_lds_dwordx4 v[194:195], off
	v_lshl_add_u64 v[194:195], s[38:39], 0, v[192:193]
	s_mov_b32 m0, s55
	s_nop 0
	global_load_lds_dwordx4 v[194:195], off
	s_mov_b64 exec, -1
	s_waitcnt vmcnt(8)
	s_waitcnt lgkmcnt(0)
	s_setprio 1
	s_barrier
	v_mfma_f32_16x16x32_bf16 v[62:65], v[126:129], v[166:169], v[62:65]
	v_mfma_f32_16x16x32_bf16 v[58:61], v[134:137], v[166:169], v[58:61]
	v_mfma_f32_16x16x32_bf16 v[46:49], v[126:129], v[174:177], v[46:49]
	v_mfma_f32_16x16x32_bf16 v[42:45], v[134:137], v[174:177], v[42:45]
	v_mfma_f32_16x16x32_bf16 v[30:33], v[126:129], v[182:185], v[30:33]
	v_mfma_f32_16x16x32_bf16 v[26:29], v[134:137], v[182:185], v[26:29]
	v_mfma_f32_16x16x32_bf16 v[14:17], v[126:129], v[208:211], v[14:17]
	v_mfma_f32_16x16x32_bf16 v[10:13], v[134:137], v[208:211], v[10:13]
	v_mfma_f32_16x16x32_bf16 v[62:65], v[130:133], v[170:173], v[62:65]
	v_mfma_f32_16x16x32_bf16 v[58:61], v[138:141], v[170:173], v[58:61]
	v_mfma_f32_16x16x32_bf16 v[46:49], v[130:133], v[178:181], v[46:49]
	v_mfma_f32_16x16x32_bf16 v[42:45], v[138:141], v[178:181], v[42:45]
	v_mfma_f32_16x16x32_bf16 v[30:33], v[130:133], v[186:189], v[30:33]
	v_mfma_f32_16x16x32_bf16 v[26:29], v[138:141], v[186:189], v[26:29]
	v_mfma_f32_16x16x32_bf16 v[14:17], v[130:133], v[212:215], v[14:17]
	v_mfma_f32_16x16x32_bf16 v[10:13], v[138:141], v[212:215], v[10:13]
	v_mfma_f32_16x16x32_bf16 v[54:57], v[142:145], v[166:169], v[54:57]
	v_mfma_f32_16x16x32_bf16 v[50:53], v[158:161], v[166:169], v[50:53]
	v_mfma_f32_16x16x32_bf16 v[38:41], v[142:145], v[174:177], v[38:41]
	v_mfma_f32_16x16x32_bf16 v[34:37], v[158:161], v[174:177], v[34:37]
	v_mfma_f32_16x16x32_bf16 v[22:25], v[142:145], v[182:185], v[22:25]
	v_mfma_f32_16x16x32_bf16 v[18:21], v[158:161], v[182:185], v[18:21]
	v_mfma_f32_16x16x32_bf16 v[6:9], v[142:145], v[208:211], v[6:9]
	v_mfma_f32_16x16x32_bf16 v[2:5], v[158:161], v[208:211], v[2:5]
	v_mfma_f32_16x16x32_bf16 v[54:57], v[146:149], v[170:173], v[54:57]
	v_mfma_f32_16x16x32_bf16 v[50:53], v[162:165], v[170:173], v[50:53]
	v_mfma_f32_16x16x32_bf16 v[38:41], v[146:149], v[178:181], v[38:41]
	v_mfma_f32_16x16x32_bf16 v[34:37], v[162:165], v[178:181], v[34:37]
	v_mfma_f32_16x16x32_bf16 v[22:25], v[146:149], v[186:189], v[22:25]
	v_mfma_f32_16x16x32_bf16 v[18:21], v[162:165], v[186:189], v[18:21]
	v_mfma_f32_16x16x32_bf16 v[6:9], v[146:149], v[212:215], v[6:9]
	v_mfma_f32_16x16x32_bf16 v[2:5], v[162:165], v[212:215], v[2:5]
	s_barrier
	s_setprio 0
	s_add_i32 s84, s84, 2
	s_add_u32 s36, s36, 0x100
	s_addc_u32 s37, s37, 0
	s_cmp_gt_u32 s84, 61
	s_cbranch_scc0 .LBB0_915

.LBB0_953:
	s_add_u32 s4, s24, s26
	s_addc_u32 s5, s25, s27
	s_add_u32 s34, s4, 0x100
	s_addc_u32 s35, s5, 0
	s_add_u32 s30, s68, s26
	s_addc_u32 s31, s69, s27
	s_add_u32 s4, s4, 0x180
	s_addc_u32 s5, s5, 0
	s_add_i32 s71, 0, 0x10000
	s_add_i32 s74, 0, 0x14000
	v_add_u32_e32 v146, s71, v229
	v_add_u32_e32 v162, s74, v229
	ds_read_b128 v[134:137], v146
	ds_read_b128 v[138:141], v146 offset:1024
	ds_read_b128 v[142:145], v146 offset:2048
	ds_read_b128 v[146:149], v146 offset:3072
	ds_read_b128 v[150:153], v162
	ds_read_b128 v[154:157], v162 offset:1024
	ds_read_b128 v[158:161], v162 offset:2048
	ds_read_b128 v[162:165], v162 offset:3072
	s_cmpk_eq_i32 s26, 0x1f00
	s_cselect_b64 s[98:99], s[6:7], -1
	s_cselect_b32 s29, s65, s5
	s_cselect_b32 s28, s59, s4
	s_cselect_b32 s31, s17, s31
	s_cselect_b32 s30, s58, s30
	s_cselect_b32 s35, s19, s35
	s_cselect_b32 s34, s57, s34
	v_lshl_add_u64 v[194:195], v[122:123], 0, s[26:27]
	s_add_i32 m0, s37, 0xc000
	ds_read_b128 v[166:169], v231
	ds_read_b128 v[170:173], v231 offset:1024
	ds_read_b128 v[174:177], v231 offset:2048
	ds_read_b128 v[178:181], v231 offset:3072
	ds_read_b128 v[182:185], v231 offset:4096
	ds_read_b128 v[186:189], v231 offset:5120
	ds_read_b128 v[190:193], v231 offset:6144
	ds_read_b128 v[212:215], v231 offset:7168
	global_load_lds_dwordx4 v[194:195], off
	v_lshl_add_u64 v[194:195], v[124:125], 0, s[26:27]
	s_add_i32 m0, s37, 0xe000
	s_nop 0
	global_load_lds_dwordx4 v[194:195], off
	s_waitcnt vmcnt(8)
	s_waitcnt lgkmcnt(0)
	s_setprio 1
	s_barrier
	v_mfma_f32_16x16x32_bf16 v[130:133], v[134:137], v[166:169], v[130:133]
	v_mfma_f32_16x16x32_bf16 v[126:129], v[142:145], v[166:169], v[126:129]
	v_mfma_f32_16x16x32_bf16 v[110:113], v[134:137], v[174:177], v[110:113]
	v_mfma_f32_16x16x32_bf16 v[106:109], v[142:145], v[174:177], v[106:109]
	v_mfma_f32_16x16x32_bf16 v[94:97], v[134:137], v[182:185], v[94:97]
	v_mfma_f32_16x16x32_bf16 v[90:93], v[142:145], v[182:185], v[90:93]
	v_mfma_f32_16x16x32_bf16 v[78:81], v[134:137], v[190:193], v[78:81]
	v_mfma_f32_16x16x32_bf16 v[74:77], v[142:145], v[190:193], v[74:77]
	v_mfma_f32_16x16x32_bf16 v[130:133], v[138:141], v[170:173], v[130:133]
	v_mfma_f32_16x16x32_bf16 v[126:129], v[146:149], v[170:173], v[126:129]
	v_mfma_f32_16x16x32_bf16 v[110:113], v[138:141], v[178:181], v[110:113]
	v_mfma_f32_16x16x32_bf16 v[106:109], v[146:149], v[178:181], v[106:109]
	v_mfma_f32_16x16x32_bf16 v[94:97], v[138:141], v[186:189], v[94:97]
	v_mfma_f32_16x16x32_bf16 v[90:93], v[146:149], v[186:189], v[90:93]
	v_mfma_f32_16x16x32_bf16 v[78:81], v[138:141], v[212:215], v[78:81]
	v_mfma_f32_16x16x32_bf16 v[74:77], v[146:149], v[212:215], v[74:77]
	v_mfma_f32_16x16x32_bf16 v[118:121], v[150:153], v[166:169], v[118:121]
	v_mfma_f32_16x16x32_bf16 v[114:117], v[158:161], v[166:169], v[114:117]
	v_mfma_f32_16x16x32_bf16 v[102:105], v[150:153], v[174:177], v[102:105]
	v_mfma_f32_16x16x32_bf16 v[98:101], v[158:161], v[174:177], v[98:101]
	v_mfma_f32_16x16x32_bf16 v[86:89], v[150:153], v[182:185], v[86:89]
	v_mfma_f32_16x16x32_bf16 v[82:85], v[158:161], v[182:185], v[82:85]
	v_mfma_f32_16x16x32_bf16 v[70:73], v[150:153], v[190:193], v[70:73]
	v_mfma_f32_16x16x32_bf16 v[66:69], v[158:161], v[190:193], v[66:69]
	v_mfma_f32_16x16x32_bf16 v[118:121], v[154:157], v[170:173], v[118:121]
	v_mfma_f32_16x16x32_bf16 v[114:117], v[162:165], v[170:173], v[114:117]
	v_mfma_f32_16x16x32_bf16 v[102:105], v[154:157], v[178:181], v[102:105]
	v_mfma_f32_16x16x32_bf16 v[98:101], v[162:165], v[178:181], v[98:101]
	v_mfma_f32_16x16x32_bf16 v[86:89], v[154:157], v[186:189], v[86:89]
	v_mfma_f32_16x16x32_bf16 v[82:85], v[162:165], v[186:189], v[82:85]
	v_mfma_f32_16x16x32_bf16 v[70:73], v[154:157], v[212:215], v[70:73]
	v_mfma_f32_16x16x32_bf16 v[66:69], v[162:165], v[212:215], v[66:69]
	s_barrier
	s_setprio 0
	s_add_i32 s4, s71, s36
	v_lshl_add_u64 v[194:195], s[30:31], 0, v[0:1]
	s_mov_b32 m0, s4
	ds_read_b128 v[166:169], v231 offset:16384
	ds_read_b128 v[170:173], v231 offset:17408
	ds_read_b128 v[174:177], v231 offset:18432
	ds_read_b128 v[178:181], v231 offset:19456
	ds_read_b128 v[182:185], v231 offset:20480
	ds_read_b128 v[186:189], v231 offset:21504
	ds_read_b128 v[190:193], v231 offset:22528
	ds_read_b128 v[212:215], v231 offset:23552
	s_mov_b64 exec, s[98:99]
	global_load_lds_dwordx4 v[194:195], off
	s_add_i32 m0, s4, 0x2000
	s_add_u32 s72, s30, 0x100000
	v_lshl_add_u64 v[198:199], s[30:31], 0, v[202:203]
	s_addc_u32 s73, s31, 0
	s_add_i32 s4, s74, s36
	global_load_lds_dwordx4 v[198:199], off
	v_lshl_add_u64 v[216:217], s[72:73], 0, v[0:1]
	s_mov_b32 m0, s4
	s_nop 0
	global_load_lds_dwordx4 v[216:217], off
	v_lshl_add_u64 v[216:217], s[72:73], 0, v[202:203]
	s_add_i32 m0, s4, 0x2000
	s_nop 0
	global_load_lds_dwordx4 v[216:217], off
	v_lshl_add_u64 v[216:217], s[34:35], 0, v[206:207]
	s_mov_b32 m0, s37
	s_nop 0
	global_load_lds_dwordx4 v[216:217], off
	v_lshl_add_u64 v[216:217], s[34:35], 0, v[204:205]
	s_mov_b32 m0, s38
	s_nop 0
	global_load_lds_dwordx4 v[216:217], off
	s_mov_b64 exec, -1
	s_waitcnt vmcnt(8)
	s_waitcnt lgkmcnt(0)
	s_setprio 1
	s_barrier
	v_mfma_f32_16x16x32_bf16 v[62:65], v[134:137], v[166:169], v[62:65]
	v_mfma_f32_16x16x32_bf16 v[58:61], v[142:145], v[166:169], v[58:61]
	v_mfma_f32_16x16x32_bf16 v[46:49], v[134:137], v[174:177], v[46:49]
	v_mfma_f32_16x16x32_bf16 v[42:45], v[142:145], v[174:177], v[42:45]
	v_mfma_f32_16x16x32_bf16 v[30:33], v[134:137], v[182:185], v[30:33]
	v_mfma_f32_16x16x32_bf16 v[26:29], v[142:145], v[182:185], v[26:29]
	v_mfma_f32_16x16x32_bf16 v[14:17], v[134:137], v[190:193], v[14:17]
	v_mfma_f32_16x16x32_bf16 v[10:13], v[142:145], v[190:193], v[10:13]
	v_mfma_f32_16x16x32_bf16 v[62:65], v[138:141], v[170:173], v[62:65]
	v_mfma_f32_16x16x32_bf16 v[58:61], v[146:149], v[170:173], v[58:61]
	v_mfma_f32_16x16x32_bf16 v[46:49], v[138:141], v[178:181], v[46:49]
	v_mfma_f32_16x16x32_bf16 v[42:45], v[146:149], v[178:181], v[42:45]
	v_mfma_f32_16x16x32_bf16 v[30:33], v[138:141], v[186:189], v[30:33]
	v_mfma_f32_16x16x32_bf16 v[26:29], v[146:149], v[186:189], v[26:29]
	v_mfma_f32_16x16x32_bf16 v[14:17], v[138:141], v[212:215], v[14:17]
	v_mfma_f32_16x16x32_bf16 v[10:13], v[146:149], v[212:215], v[10:13]
	v_mfma_f32_16x16x32_bf16 v[54:57], v[150:153], v[166:169], v[54:57]
	v_mfma_f32_16x16x32_bf16 v[50:53], v[158:161], v[166:169], v[50:53]
	v_mfma_f32_16x16x32_bf16 v[38:41], v[150:153], v[174:177], v[38:41]
	v_mfma_f32_16x16x32_bf16 v[34:37], v[158:161], v[174:177], v[34:37]
	v_mfma_f32_16x16x32_bf16 v[22:25], v[150:153], v[182:185], v[22:25]
	v_mfma_f32_16x16x32_bf16 v[18:21], v[158:161], v[182:185], v[18:21]
	v_mfma_f32_16x16x32_bf16 v[6:9], v[150:153], v[190:193], v[6:9]
	v_mfma_f32_16x16x32_bf16 v[2:5], v[158:161], v[190:193], v[2:5]
	v_mfma_f32_16x16x32_bf16 v[54:57], v[154:157], v[170:173], v[54:57]
	v_mfma_f32_16x16x32_bf16 v[50:53], v[162:165], v[170:173], v[50:53]
	v_mfma_f32_16x16x32_bf16 v[38:41], v[154:157], v[178:181], v[38:41]
	v_mfma_f32_16x16x32_bf16 v[34:37], v[162:165], v[178:181], v[34:37]
	v_mfma_f32_16x16x32_bf16 v[22:25], v[154:157], v[186:189], v[22:25]
	v_mfma_f32_16x16x32_bf16 v[18:21], v[162:165], v[186:189], v[18:21]
	v_mfma_f32_16x16x32_bf16 v[6:9], v[154:157], v[212:215], v[6:9]
	v_mfma_f32_16x16x32_bf16 v[2:5], v[162:165], v[212:215], v[2:5]
	s_barrier
	s_setprio 0
	s_add_i32 s4, 0, 0x18000
	s_add_i32 s5, 0, 0x1c000
	v_add_u32_e32 v146, s4, v229
	v_add_u32_e32 v162, s5, v229
	ds_read_b128 v[134:137], v146
	ds_read_b128 v[138:141], v146 offset:1024
	ds_read_b128 v[142:145], v146 offset:2048
	ds_read_b128 v[146:149], v146 offset:3072
	ds_read_b128 v[150:153], v162
	ds_read_b128 v[154:157], v162 offset:1024
	ds_read_b128 v[158:161], v162 offset:2048
	ds_read_b128 v[162:165], v162 offset:3072
	s_add_u32 s34, s34, 0x100000
	s_addc_u32 s35, s35, 0
	s_mov_b32 m0, s39
	v_lshl_add_u64 v[216:217], s[34:35], 0, v[206:207]
	ds_read_b128 v[166:169], v231 offset:32768
	ds_read_b128 v[170:173], v231 offset:33792
	ds_read_b128 v[174:177], v231 offset:34816
	ds_read_b128 v[178:181], v231 offset:35840
	ds_read_b128 v[182:185], v231 offset:36864
	ds_read_b128 v[186:189], v231 offset:37888
	ds_read_b128 v[190:193], v231 offset:38912
	ds_read_b128 v[212:215], v231 offset:39936
	s_mov_b64 exec, s[98:99]
	global_load_lds_dwordx4 v[216:217], off
	v_lshl_add_u64 v[216:217], s[34:35], 0, v[204:205]
	s_mov_b32 m0, s40
	s_nop 0
	global_load_lds_dwordx4 v[216:217], off
	s_mov_b64 exec, -1
	s_waitcnt vmcnt(8)
	s_waitcnt lgkmcnt(0)
	s_setprio 1
	s_barrier
	v_mfma_f32_16x16x32_bf16 v[130:133], v[134:137], v[166:169], v[130:133]
	v_mfma_f32_16x16x32_bf16 v[126:129], v[142:145], v[166:169], v[126:129]
	v_mfma_f32_16x16x32_bf16 v[110:113], v[134:137], v[174:177], v[110:113]
	v_mfma_f32_16x16x32_bf16 v[106:109], v[142:145], v[174:177], v[106:109]
	v_mfma_f32_16x16x32_bf16 v[94:97], v[134:137], v[182:185], v[94:97]
	v_mfma_f32_16x16x32_bf16 v[90:93], v[142:145], v[182:185], v[90:93]
	v_mfma_f32_16x16x32_bf16 v[78:81], v[134:137], v[190:193], v[78:81]
	v_mfma_f32_16x16x32_bf16 v[74:77], v[142:145], v[190:193], v[74:77]
	v_mfma_f32_16x16x32_bf16 v[130:133], v[138:141], v[170:173], v[130:133]
	v_mfma_f32_16x16x32_bf16 v[126:129], v[146:149], v[170:173], v[126:129]
	v_mfma_f32_16x16x32_bf16 v[110:113], v[138:141], v[178:181], v[110:113]
	v_mfma_f32_16x16x32_bf16 v[106:109], v[146:149], v[178:181], v[106:109]
	v_mfma_f32_16x16x32_bf16 v[94:97], v[138:141], v[186:189], v[94:97]
	v_mfma_f32_16x16x32_bf16 v[90:93], v[146:149], v[186:189], v[90:93]
	v_mfma_f32_16x16x32_bf16 v[78:81], v[138:141], v[212:215], v[78:81]
	v_mfma_f32_16x16x32_bf16 v[74:77], v[146:149], v[212:215], v[74:77]
	v_mfma_f32_16x16x32_bf16 v[118:121], v[150:153], v[166:169], v[118:121]
	v_mfma_f32_16x16x32_bf16 v[114:117], v[158:161], v[166:169], v[114:117]
	v_mfma_f32_16x16x32_bf16 v[102:105], v[150:153], v[174:177], v[102:105]
	v_mfma_f32_16x16x32_bf16 v[98:101], v[158:161], v[174:177], v[98:101]
	v_mfma_f32_16x16x32_bf16 v[86:89], v[150:153], v[182:185], v[86:89]
	v_mfma_f32_16x16x32_bf16 v[82:85], v[158:161], v[182:185], v[82:85]
	v_mfma_f32_16x16x32_bf16 v[70:73], v[150:153], v[190:193], v[70:73]
	v_mfma_f32_16x16x32_bf16 v[66:69], v[158:161], v[190:193], v[66:69]
	v_mfma_f32_16x16x32_bf16 v[118:121], v[154:157], v[170:173], v[118:121]
	v_mfma_f32_16x16x32_bf16 v[114:117], v[162:165], v[170:173], v[114:117]
	v_mfma_f32_16x16x32_bf16 v[102:105], v[154:157], v[178:181], v[102:105]
	v_mfma_f32_16x16x32_bf16 v[98:101], v[162:165], v[178:181], v[98:101]
	v_mfma_f32_16x16x32_bf16 v[86:89], v[154:157], v[186:189], v[86:89]
	v_mfma_f32_16x16x32_bf16 v[82:85], v[162:165], v[186:189], v[82:85]
	v_mfma_f32_16x16x32_bf16 v[70:73], v[154:157], v[212:215], v[70:73]
	v_mfma_f32_16x16x32_bf16 v[66:69], v[162:165], v[212:215], v[66:69]
	s_barrier
	s_setprio 0
	s_add_i32 s4, s4, s36
	v_lshl_add_u64 v[194:195], v[194:195], 0, s[90:91]
	s_mov_b32 m0, s4
	ds_read_b128 v[166:169], v231 offset:49152
	ds_read_b128 v[170:173], v231 offset:50176
	ds_read_b128 v[174:177], v231 offset:51200
	ds_read_b128 v[178:181], v231 offset:52224
	ds_read_b128 v[182:185], v231 offset:53248
	ds_read_b128 v[186:189], v231 offset:54272
	ds_read_b128 v[190:193], v231 offset:55296
	ds_read_b128 v[212:215], v231 offset:56320
	s_mov_b64 exec, s[98:99]
	global_load_lds_dwordx4 v[194:195], off
	s_add_i32 m0, s4, 0x2000
	s_add_u32 s30, s30, 0x100080
	v_lshl_add_u64 v[194:195], v[198:199], 0, s[90:91]
	s_addc_u32 s31, s31, 0
	s_add_i32 s4, s5, s36
	global_load_lds_dwordx4 v[194:195], off
	v_lshl_add_u64 v[194:195], s[30:31], 0, v[0:1]
	s_mov_b32 m0, s4
	s_nop 0
	global_load_lds_dwordx4 v[194:195], off
	v_lshl_add_u64 v[194:195], s[30:31], 0, v[202:203]
	s_add_i32 m0, s4, 0x2000
	s_nop 0
	global_load_lds_dwordx4 v[194:195], off
	v_lshl_add_u64 v[194:195], s[28:29], 0, v[206:207]
	s_mov_b32 m0, s41
	s_nop 0
	global_load_lds_dwordx4 v[194:195], off
	v_lshl_add_u64 v[194:195], s[28:29], 0, v[204:205]
	s_mov_b32 m0, s42
	s_nop 0
	global_load_lds_dwordx4 v[194:195], off
	s_mov_b64 exec, -1
	s_waitcnt vmcnt(8)
	s_waitcnt lgkmcnt(0)
	s_setprio 1
	s_barrier
	v_mfma_f32_16x16x32_bf16 v[62:65], v[134:137], v[166:169], v[62:65]
	v_mfma_f32_16x16x32_bf16 v[58:61], v[142:145], v[166:169], v[58:61]
	v_mfma_f32_16x16x32_bf16 v[46:49], v[134:137], v[174:177], v[46:49]
	v_mfma_f32_16x16x32_bf16 v[42:45], v[142:145], v[174:177], v[42:45]
	v_mfma_f32_16x16x32_bf16 v[30:33], v[134:137], v[182:185], v[30:33]
	v_mfma_f32_16x16x32_bf16 v[26:29], v[142:145], v[182:185], v[26:29]
	v_mfma_f32_16x16x32_bf16 v[14:17], v[134:137], v[190:193], v[14:17]
	v_mfma_f32_16x16x32_bf16 v[10:13], v[142:145], v[190:193], v[10:13]
	v_mfma_f32_16x16x32_bf16 v[62:65], v[138:141], v[170:173], v[62:65]
	v_mfma_f32_16x16x32_bf16 v[58:61], v[146:149], v[170:173], v[58:61]
	v_mfma_f32_16x16x32_bf16 v[46:49], v[138:141], v[178:181], v[46:49]
	v_mfma_f32_16x16x32_bf16 v[42:45], v[146:149], v[178:181], v[42:45]
	v_mfma_f32_16x16x32_bf16 v[30:33], v[138:141], v[186:189], v[30:33]
	v_mfma_f32_16x16x32_bf16 v[26:29], v[146:149], v[186:189], v[26:29]
	v_mfma_f32_16x16x32_bf16 v[14:17], v[138:141], v[212:215], v[14:17]
	v_mfma_f32_16x16x32_bf16 v[10:13], v[146:149], v[212:215], v[10:13]
	v_mfma_f32_16x16x32_bf16 v[54:57], v[150:153], v[166:169], v[54:57]
	v_mfma_f32_16x16x32_bf16 v[50:53], v[158:161], v[166:169], v[50:53]
	v_mfma_f32_16x16x32_bf16 v[38:41], v[150:153], v[174:177], v[38:41]
	v_mfma_f32_16x16x32_bf16 v[34:37], v[158:161], v[174:177], v[34:37]
	v_mfma_f32_16x16x32_bf16 v[22:25], v[150:153], v[182:185], v[22:25]
	v_mfma_f32_16x16x32_bf16 v[18:21], v[158:161], v[182:185], v[18:21]
	v_mfma_f32_16x16x32_bf16 v[6:9], v[150:153], v[190:193], v[6:9]
	v_mfma_f32_16x16x32_bf16 v[2:5], v[158:161], v[190:193], v[2:5]
	v_mfma_f32_16x16x32_bf16 v[54:57], v[154:157], v[170:173], v[54:57]
	v_mfma_f32_16x16x32_bf16 v[50:53], v[162:165], v[170:173], v[50:53]
	v_mfma_f32_16x16x32_bf16 v[38:41], v[154:157], v[178:181], v[38:41]
	v_mfma_f32_16x16x32_bf16 v[34:37], v[162:165], v[178:181], v[34:37]
	v_mfma_f32_16x16x32_bf16 v[22:25], v[154:157], v[186:189], v[22:25]
	v_mfma_f32_16x16x32_bf16 v[18:21], v[162:165], v[186:189], v[18:21]
	v_mfma_f32_16x16x32_bf16 v[6:9], v[154:157], v[212:215], v[6:9]
	v_mfma_f32_16x16x32_bf16 v[2:5], v[162:165], v[212:215], v[2:5]
	s_barrier
	s_setprio 0
	s_add_i32 s70, s70, 2
	s_add_u32 s26, s26, 0x100
	s_addc_u32 s27, s27, 0
	s_cmp_gt_u32 s70, 61
	s_cbranch_scc0 .LBB0_953
